# v4(DMA issue spread in QK chain) + EpiRes epilogues: base row loads software-pipelined 2 row-groups ahead with counted vmcnt
# speedup vs baseline: 1.0079x; 1.0004x over previous
.LBB0_309:
	s_mov_b32 s77, s74
	v_add3_u32 v215, s77, v209, v208
	v_add3_u32 v216, s77, v210, v208
	v_add3_u32 v233, s77, v211, v208
	v_add3_u32 v254, s77, v212, v208
	ds_read_b128 v[234:237], v215 offset:49152
	ds_read_b128 v[238:241], v215 offset:57344
	ds_read_b128 v[242:245], v216 offset:49152
	ds_read_b128 v[246:249], v216 offset:57344
	ds_read_b128 v[250:253], v233 offset:49152
	s_add_u32 s4, s70, 0xffffc000
	s_mov_b32 s74, s72
	s_addc_u32 s5, s71, -1
	s_add_i32 s72, s72, s42
	s_setprio 1
	s_waitcnt lgkmcnt(4)
	v_mfma_f32_32x32x16_bf16 v[112:127], v[234:237], v[188:191], 0
	ds_read_b128 v[234:237], v233 offset:57344
	v_add_f32_e32 v1, 0, v230
	v_add_f32_e32 v1, v232, v1
	v_add_f32_e32 v1, v228, v1
	v_add_f32_e32 v1, v231, v1
	v_add_f32_e32 v1, v226, v1
	v_add_f32_e32 v1, v229, v1
	s_waitcnt lgkmcnt(4)
	v_mfma_f32_32x32x16_bf16 v[96:111], v[238:241], v[188:191], 0
	ds_read_b128 v[238:241], v254 offset:49152
	v_add_f32_e32 v1, v225, v1
	v_add_f32_e32 v1, v227, v1
	v_add_f32_e32 v1, v222, v1
	v_add_f32_e32 v1, v224, v1
	v_add_f32_e32 v1, v220, v1
	s_waitcnt lgkmcnt(4)
	v_mfma_f32_32x32x16_bf16 v[112:127], v[242:245], v[184:187], v[112:127]
	ds_read_b128 v[242:245], v254 offset:57344
	s_mov_b32 s73, m0
	s_mov_b32 m0, s72
	s_nop 0
	global_load_lds_dwordx4 v197, s[4:5]
	s_mov_b32 m0, s73
	v_add_f32_e32 v1, v223, v1
	v_exp_f32_e32 v2, v128
	v_add_f32_e32 v1, v218, v1
	v_exp_f32_e32 v12, v129
	s_waitcnt lgkmcnt(4)
	v_mfma_f32_32x32x16_bf16 v[96:111], v[246:249], v[184:187], v[96:111]
	ds_read_b128 v[246:249], v215 offset:49280
	v_add_f32_e32 v1, v221, v1
	v_exp_f32_e32 v13, v130
	v_add_f32_e32 v1, v217, v1
	v_exp_f32_e32 v14, v131
	s_waitcnt lgkmcnt(4)
	v_mfma_f32_32x32x16_bf16 v[112:127], v[250:253], v[180:183], v[112:127]
	ds_read_b128 v[250:253], v215 offset:57472
	v_add_f32_e32 v1, v219, v1
	v_exp_f32_e32 v15, v132
	v_add_f32_e32 v1, v2, v1
	v_exp_f32_e32 v18, v133
	s_waitcnt lgkmcnt(4)
	v_mfma_f32_32x32x16_bf16 v[96:111], v[234:237], v[180:183], v[96:111]
	ds_read_b128 v[234:237], v216 offset:49280
	s_addk_i32 s72, 0x400
	s_mov_b32 s73, m0
	s_mov_b32 m0, s72
	s_nop 0
	global_load_lds_dwordx4 v198, s[4:5]
	s_mov_b32 m0, s73
	v_add_f32_e32 v1, v12, v1
	v_exp_f32_e32 v19, v134
	v_add_f32_e32 v1, v13, v1
	s_waitcnt lgkmcnt(4)
	v_mfma_f32_32x32x16_bf16 v[112:127], v[238:241], v[176:179], v[112:127]
	ds_read_b128 v[238:241], v216 offset:57472
	v_exp_f32_e32 v20, v135
	v_add_f32_e32 v1, v14, v1
	v_exp_f32_e32 v21, v136
	v_add_f32_e32 v1, v15, v1
	s_waitcnt lgkmcnt(4)
	v_mfma_f32_32x32x16_bf16 v[96:111], v[242:245], v[176:179], v[96:111]
	ds_read_b128 v[242:245], v233 offset:49280
	v_exp_f32_e32 v22, v137
	v_add_f32_e32 v1, v18, v1
	v_exp_f32_e32 v23, v138
	v_add_f32_e32 v1, v19, v1
	s_waitcnt lgkmcnt(4)
	v_mfma_f32_32x32x16_bf16 v[112:127], v[246:249], v[172:175], v[112:127]
	ds_read_b128 v[246:249], v233 offset:57472
	s_add_i32 s4, s69, s97
	s_mov_b32 s5, m0
	s_mov_b32 m0, s4
	s_nop 0
	global_load_lds_dwordx4 v199, s[56:57]
	s_mov_b32 m0, s5
	v_exp_f32_e32 v24, v139
	v_add_f32_e32 v1, v20, v1
	v_exp_f32_e32 v25, v140
	v_add_f32_e32 v1, v21, v1
	s_waitcnt lgkmcnt(4)
	v_mfma_f32_32x32x16_bf16 v[96:111], v[250:253], v[172:175], v[96:111]
	ds_read_b128 v[250:253], v254 offset:49280
	v_exp_f32_e32 v26, v141
	v_add_f32_e32 v1, v22, v1
	v_exp_f32_e32 v27, v142
	v_add_f32_e32 v1, v23, v1
	s_waitcnt lgkmcnt(4)
	v_mfma_f32_32x32x16_bf16 v[112:127], v[234:237], v[168:171], v[112:127]
	ds_read_b128 v[234:237], v254 offset:57472
	v_exp_f32_e32 v28, v143
	v_add_f32_e32 v1, v24, v1
	v_add_f32_e32 v1, v25, v1
	v_add_f32_e32 v1, v26, v1
	s_waitcnt lgkmcnt(4)
	v_mfma_f32_32x32x16_bf16 v[96:111], v[238:241], v[168:171], v[96:111]
	s_addk_i32 s4, 0x400
	s_mov_b32 s5, m0
	s_mov_b32 m0, s4
	s_nop 0
	global_load_lds_dwordx4 v200, s[56:57]
	s_mov_b32 m0, s5
	v_add_f32_e32 v1, v27, v1
	v_add_f32_e32 v1, v28, v1
	v_mov_b32_e32 v3, v1
	v_cvt_pk_bf16_f32 v4, v230, v232
	v_cvt_pk_bf16_f32 v5, v228, v231
	v_cvt_pk_bf16_f32 v6, v226, v229
	s_waitcnt lgkmcnt(3)
	v_mfma_f32_32x32x16_bf16 v[112:127], v[242:245], v[164:167], v[112:127]
	s_nop 1
	v_permlane32_swap_b32_e32 v1, v3
	v_cvt_pk_bf16_f32 v7, v225, v227
	v_permlane32_swap_b32_e32 v4, v6
	v_cvt_pk_bf16_f32 v8, v222, v224
	v_cvt_pk_bf16_f32 v9, v220, v223
	s_waitcnt lgkmcnt(2)
	v_mfma_f32_32x32x16_bf16 v[96:111], v[246:249], v[164:167], v[96:111]
	v_cvt_pk_bf16_f32 v10, v218, v221
	v_cvt_pk_bf16_f32 v11, v217, v219
	v_cvt_pk_bf16_f32 v12, v2, v12
	v_cvt_pk_bf16_f32 v13, v13, v14
	v_cvt_pk_bf16_f32 v14, v15, v18
	v_cvt_pk_bf16_f32 v15, v19, v20
	s_waitcnt lgkmcnt(1)
	v_mfma_f32_32x32x16_bf16 v[112:127], v[250:253], v[160:163], v[112:127]
	v_cvt_pk_bf16_f32 v18, v21, v22
	v_cvt_pk_bf16_f32 v19, v23, v24
	v_cvt_pk_bf16_f32 v20, v25, v26
	v_cvt_pk_bf16_f32 v21, v27, v28
	v_permlane32_swap_b32_e32 v5, v7
	s_waitcnt lgkmcnt(0)
	v_mfma_f32_32x32x16_bf16 v[96:111], v[234:237], v[160:163], v[96:111]
	v_permlane32_swap_b32_e32 v8, v10
	v_permlane32_swap_b32_e32 v9, v11
	v_permlane32_swap_b32_e32 v12, v14
	v_permlane32_swap_b32_e32 v13, v15
	v_permlane32_swap_b32_e32 v18, v20
	v_permlane32_swap_b32_e32 v19, v21
	s_setprio 0
	v_add_u32_e32 v2, s74, v206
	ds_read_b64_tr_b16 v[22:23], v2 offset:0
	ds_read_b64_tr_b16 v[24:25], v2 offset:0x800
	ds_read_b64_tr_b16 v[26:27], v2 offset:0x1000
	ds_read_b64_tr_b16 v[28:29], v2 offset:0x1800
	ds_read_b64_tr_b16 v[128:129], v2 offset:0x2000
	ds_read_b64_tr_b16 v[130:131], v2 offset:0x2800
	ds_read_b64_tr_b16 v[132:133], v2 offset:0x3000
	ds_read_b64_tr_b16 v[134:135], v2 offset:0x3800
	s_waitcnt lgkmcnt(0)
	s_nop 0
	v_mfma_f32_32x32x16_bf16 v[32:47], v[4:7], v[22:25], v[32:47]
	ds_read_b64_tr_b16 v[22:23], v2 offset:0x200
	ds_read_b64_tr_b16 v[24:25], v2 offset:0xa00
	v_mfma_f32_32x32x16_bf16 v[32:47], v[8:11], v[26:29], v[32:47]
	ds_read_b64_tr_b16 v[26:27], v2 offset:0x1200
	ds_read_b64_tr_b16 v[28:29], v2 offset:0x1a00
	v_mfma_f32_32x32x16_bf16 v[32:47], v[12:15], v[128:131], v[32:47]
	ds_read_b64_tr_b16 v[128:129], v2 offset:0x2200
	ds_read_b64_tr_b16 v[130:131], v2 offset:0x2a00
	v_mfma_f32_32x32x16_bf16 v[32:47], v[18:21], v[132:135], v[32:47]
	ds_read_b64_tr_b16 v[132:133], v2 offset:0x3200
	ds_read_b64_tr_b16 v[134:135], v2 offset:0x3a00
	s_waitcnt lgkmcnt(0)
	v_mfma_f32_32x32x16_bf16 v[48:63], v[4:7], v[22:25], v[48:63]
	ds_read_b64_tr_b16 v[22:23], v2 offset:0x400
	ds_read_b64_tr_b16 v[24:25], v2 offset:0xc00
	v_mfma_f32_32x32x16_bf16 v[48:63], v[8:11], v[26:29], v[48:63]
	ds_read_b64_tr_b16 v[26:27], v2 offset:0x1400
	ds_read_b64_tr_b16 v[28:29], v2 offset:0x1c00
	v_mfma_f32_32x32x16_bf16 v[48:63], v[12:15], v[128:131], v[48:63]
	ds_read_b64_tr_b16 v[128:129], v2 offset:0x2400
	ds_read_b64_tr_b16 v[130:131], v2 offset:0x2c00
	v_mfma_f32_32x32x16_bf16 v[48:63], v[18:21], v[132:135], v[48:63]
	ds_read_b64_tr_b16 v[132:133], v2 offset:0x3400
	ds_read_b64_tr_b16 v[134:135], v2 offset:0x3c00
	s_waitcnt lgkmcnt(0)
	v_mfma_f32_32x32x16_bf16 v[64:79], v[4:7], v[22:25], v[64:79]
	ds_read_b64_tr_b16 v[22:23], v2 offset:0x600
	ds_read_b64_tr_b16 v[24:25], v2 offset:0xe00
	v_mfma_f32_32x32x16_bf16 v[64:79], v[8:11], v[26:29], v[64:79]
	ds_read_b64_tr_b16 v[26:27], v2 offset:0x1600
	ds_read_b64_tr_b16 v[28:29], v2 offset:0x1e00
	v_mfma_f32_32x32x16_bf16 v[64:79], v[12:15], v[128:131], v[64:79]
	ds_read_b64_tr_b16 v[128:129], v2 offset:0x2600
	ds_read_b64_tr_b16 v[130:131], v2 offset:0x2e00
	v_mfma_f32_32x32x16_bf16 v[64:79], v[18:21], v[132:135], v[64:79]
	ds_read_b64_tr_b16 v[132:133], v2 offset:0x3600
	ds_read_b64_tr_b16 v[134:135], v2 offset:0x3e00
	s_waitcnt lgkmcnt(0)
	v_mfma_f32_32x32x16_bf16 v[80:95], v[4:7], v[22:25], v[80:95]
	v_max_f32_e32 v2, v113, v113
	v_max_f32_e32 v4, v112, v112
	v_max_f32_e32 v2, v4, v2
	v_max3_f32 v2, v2, v114, v115
	v_max3_f32 v2, v2, v116, v117
	v_max3_f32 v2, v2, v118, v119
	v_max3_f32 v2, v2, v120, v121
	v_max3_f32 v2, v2, v122, v123
	v_max3_f32 v2, v2, v124, v125
	v_max3_f32 v2, v2, v126, v127
	v_mfma_f32_32x32x16_bf16 v[80:95], v[8:11], v[26:29], v[80:95]
	v_max3_f32 v2, v2, v96, v97
	v_max3_f32 v2, v2, v98, v99
	v_max3_f32 v2, v2, v100, v101
	v_max3_f32 v2, v2, v102, v103
	v_max3_f32 v2, v2, v104, v105
	v_max3_f32 v2, v2, v106, v107
	v_max3_f32 v2, v2, v108, v109
	v_max3_f32 v2, v2, v110, v111
	v_mfma_f32_32x32x16_bf16 v[80:95], v[12:15], v[128:131], v[80:95]
	v_mov_b32_e32 v4, v2
	s_nop 1
	v_permlane32_swap_b32_e32 v2, v4
	v_max_f32_e32 v4, v4, v4
	v_max_f32_e32 v2, v2, v2
	v_max_f32_e32 v2, v2, v4
	v_sub_f32_e32 v4, v2, v214
	v_mul_f32_e32 v4, 0x3db504f3, v4
	v_cmp_ge_f32_e32 vcc, s84, v4
	v_max_f32_e32 v4, v214, v214
	v_max_f32_e32 v2, v4, v2
	v_mfma_f32_32x32x16_bf16 v[80:95], v[18:21], v[132:135], v[80:95]
	v_sub_f32_e32 v4, v214, v2
	v_mul_f32_e32 v4, 0x3e0293ee, v4
	v_exp_f32_e32 v4, v4
	s_cmp_eq_u64 vcc, exec
	s_cselect_b64 s[4:5], -1, 0
	v_cndmask_b32_e64 v4, v4, 1.0, s[4:5]
	v_cmp_gt_f32_e32 vcc, 1.0, v4
	s_cbranch_vccz .LBB0_313
	s_and_saveexec_b64 s[72:73], s[2:3]
	ds_write_b32 v204, v4 offset:128
	s_or_b64 exec, exec, s[72:73]
	s_waitcnt lgkmcnt(0)
	ds_read_b128 v[6:9], v203 offset:224
	ds_read_b128 v[10:13], v203 offset:192
	ds_read_b128 v[18:21], v203 offset:160
	ds_read_b128 v[22:25], v203 offset:128
	s_waitcnt lgkmcnt(3)
	v_pk_mul_f32 v[46:47], v[46:47], v[8:9]
	s_waitcnt lgkmcnt(2)
	v_pk_mul_f32 v[42:43], v[42:43], v[12:13]
	s_waitcnt lgkmcnt(1)
	v_pk_mul_f32 v[38:39], v[38:39], v[20:21]
	s_waitcnt lgkmcnt(0)
	v_pk_mul_f32 v[34:35], v[34:35], v[24:25]
	v_pk_mul_f32 v[44:45], v[44:45], v[6:7]
	v_pk_mul_f32 v[40:41], v[40:41], v[10:11]
	v_pk_mul_f32 v[36:37], v[36:37], v[18:19]
	v_pk_mul_f32 v[32:33], v[32:33], v[22:23]
	v_pk_mul_f32 v[62:63], v[62:63], v[8:9]
	v_pk_mul_f32 v[58:59], v[58:59], v[12:13]
	v_pk_mul_f32 v[54:55], v[54:55], v[20:21]
	v_pk_mul_f32 v[50:51], v[50:51], v[24:25]
	v_pk_mul_f32 v[60:61], v[60:61], v[6:7]
	v_pk_mul_f32 v[56:57], v[56:57], v[10:11]
	v_pk_mul_f32 v[52:53], v[52:53], v[18:19]
	v_pk_mul_f32 v[48:49], v[48:49], v[22:23]
	v_pk_mul_f32 v[78:79], v[78:79], v[8:9]
	v_pk_mul_f32 v[74:75], v[74:75], v[12:13]
	v_pk_mul_f32 v[70:71], v[70:71], v[20:21]
	v_pk_mul_f32 v[66:67], v[66:67], v[24:25]
	v_pk_mul_f32 v[76:77], v[76:77], v[6:7]
	v_pk_mul_f32 v[72:73], v[72:73], v[10:11]
	v_pk_mul_f32 v[68:69], v[68:69], v[18:19]
	v_pk_mul_f32 v[64:65], v[64:65], v[22:23]
	v_pk_mul_f32 v[94:95], v[94:95], v[8:9]
	v_pk_mul_f32 v[90:91], v[90:91], v[12:13]
	v_pk_mul_f32 v[86:87], v[86:87], v[20:21]
	v_pk_mul_f32 v[82:83], v[82:83], v[24:25]
	v_pk_mul_f32 v[92:93], v[92:93], v[6:7]
	v_pk_mul_f32 v[88:89], v[88:89], v[10:11]
	v_pk_mul_f32 v[84:85], v[84:85], v[18:19]
	v_pk_mul_f32 v[80:81], v[80:81], v[22:23]
.LBB0_313:
	v_cndmask_b32_e64 v2, v2, v214, s[4:5]
	s_waitcnt vmcnt(4) lgkmcnt(0)
	s_barrier
	v_add3_u32 v215, s69, v209, v208
	v_add3_u32 v216, s69, v210, v208
	v_add3_u32 v233, s69, v211, v208
	v_add3_u32 v254, s69, v212, v208
	ds_read_b128 v[234:237], v215 offset:49152
	ds_read_b128 v[238:241], v215 offset:57344
	ds_read_b128 v[242:245], v216 offset:49152
	ds_read_b128 v[246:249], v216 offset:57344
	ds_read_b128 v[250:253], v233 offset:49152
	v_mul_f32_e32 v5, 0xbe0293ee, v2
	v_fmamk_f32 v6, v112, 0x3e0293ee, v5
	v_fmamk_f32 v7, v113, 0x3e0293ee, v5
	v_fmamk_f32 v8, v114, 0x3e0293ee, v5
	v_fmamk_f32 v9, v115, 0x3e0293ee, v5
	v_fmamk_f32 v10, v116, 0x3e0293ee, v5
	v_fmamk_f32 v11, v117, 0x3e0293ee, v5
	v_fmamk_f32 v12, v118, 0x3e0293ee, v5
	v_fmamk_f32 v13, v119, 0x3e0293ee, v5
	v_fmamk_f32 v14, v120, 0x3e0293ee, v5
	v_fmamk_f32 v15, v121, 0x3e0293ee, v5
	v_fmamk_f32 v18, v122, 0x3e0293ee, v5
	v_fmamk_f32 v19, v123, 0x3e0293ee, v5
	v_fmamk_f32 v20, v124, 0x3e0293ee, v5
	v_fmamk_f32 v21, v125, 0x3e0293ee, v5
	v_fmamk_f32 v22, v126, 0x3e0293ee, v5
	v_fmamk_f32 v23, v127, 0x3e0293ee, v5
	v_fmamk_f32 v24, v96, 0x3e0293ee, v5
	v_fmamk_f32 v25, v97, 0x3e0293ee, v5
	v_fmamk_f32 v26, v98, 0x3e0293ee, v5
	v_fmamk_f32 v27, v99, 0x3e0293ee, v5
	v_fmamk_f32 v28, v100, 0x3e0293ee, v5
	v_fmamk_f32 v29, v101, 0x3e0293ee, v5
	v_fmamk_f32 v30, v102, 0x3e0293ee, v5
	v_fmamk_f32 v31, v103, 0x3e0293ee, v5
	v_fmamk_f32 v128, v104, 0x3e0293ee, v5
	v_fmamk_f32 v129, v105, 0x3e0293ee, v5
	v_fmamk_f32 v130, v106, 0x3e0293ee, v5
	v_fmamk_f32 v131, v107, 0x3e0293ee, v5
	v_fmamk_f32 v132, v108, 0x3e0293ee, v5
	v_fmamk_f32 v133, v109, 0x3e0293ee, v5
	v_fmamk_f32 v134, v110, 0x3e0293ee, v5
	v_fmac_f32_e32 v5, 0x3e0293ee, v111
	s_setprio 1
	s_waitcnt lgkmcnt(4)
	v_mfma_f32_32x32x16_bf16 v[112:127], v[234:237], v[188:191], 0
	ds_read_b128 v[234:237], v233 offset:57344
	v_exp_f32_e32 v135, v6
	v_exp_f32_e32 v136, v7
	v_exp_f32_e32 v137, v8
	v_exp_f32_e32 v138, v9
	s_waitcnt lgkmcnt(4)
	v_mfma_f32_32x32x16_bf16 v[96:111], v[238:241], v[188:191], 0
	ds_read_b128 v[238:241], v254 offset:49152
	v_exp_f32_e32 v10, v10
	v_exp_f32_e32 v11, v11
	v_exp_f32_e32 v12, v12
	v_exp_f32_e32 v13, v13
	s_waitcnt lgkmcnt(4)
	v_mfma_f32_32x32x16_bf16 v[112:127], v[242:245], v[184:187], v[112:127]
	ds_read_b128 v[242:245], v254 offset:57344
	s_add_i32 s4, s77, s42
	s_mov_b32 s5, m0
	s_mov_b32 m0, s4
	s_nop 0
	global_load_lds_dwordx4 v197, s[70:71]
	s_mov_b32 m0, s5
	v_exp_f32_e32 v14, v14
	v_exp_f32_e32 v15, v15
	v_exp_f32_e32 v18, v18
	s_waitcnt lgkmcnt(4)
	v_mfma_f32_32x32x16_bf16 v[96:111], v[246:249], v[184:187], v[96:111]
	ds_read_b128 v[246:249], v215 offset:49280
	v_exp_f32_e32 v19, v19
	v_exp_f32_e32 v20, v20
	v_exp_f32_e32 v21, v21
	v_exp_f32_e32 v22, v22
	s_waitcnt lgkmcnt(4)
	v_mfma_f32_32x32x16_bf16 v[112:127], v[250:253], v[180:183], v[112:127]
	ds_read_b128 v[250:253], v215 offset:57472
	v_exp_f32_e32 v23, v23
	v_exp_f32_e32 v7, v24
	v_exp_f32_e32 v24, v25
	v_exp_f32_e32 v25, v26
	s_waitcnt lgkmcnt(4)
	v_mfma_f32_32x32x16_bf16 v[96:111], v[234:237], v[180:183], v[96:111]
	ds_read_b128 v[234:237], v216 offset:49280
	s_addk_i32 s4, 0x400
	s_mov_b32 s5, m0
	s_mov_b32 m0, s4
	s_nop 0
	global_load_lds_dwordx4 v198, s[70:71]
	s_mov_b32 m0, s5
	v_exp_f32_e32 v26, v27
	v_exp_f32_e32 v27, v28
	v_exp_f32_e32 v28, v29
	v_exp_f32_e32 v29, v30
	s_waitcnt lgkmcnt(4)
	v_mfma_f32_32x32x16_bf16 v[112:127], v[238:241], v[176:179], v[112:127]
	ds_read_b128 v[238:241], v216 offset:57472
	v_exp_f32_e32 v30, v31
	v_exp_f32_e32 v31, v128
	v_exp_f32_e32 v128, v129
	v_exp_f32_e32 v129, v130
	s_waitcnt lgkmcnt(4)
	v_mfma_f32_32x32x16_bf16 v[96:111], v[242:245], v[176:179], v[96:111]
	ds_read_b128 v[242:245], v233 offset:49280
	v_exp_f32_e32 v130, v131
	v_exp_f32_e32 v131, v132
	v_exp_f32_e32 v132, v133
	v_exp_f32_e32 v133, v134
	s_waitcnt lgkmcnt(4)
	v_mfma_f32_32x32x16_bf16 v[112:127], v[246:249], v[172:175], v[112:127]
	ds_read_b128 v[246:249], v233 offset:57472
	s_add_u32 s4, s56, 0x4000
	s_addc_u32 s5, s57, 0
	s_add_i32 s72, s74, s97
	s_mov_b32 s73, m0
	s_mov_b32 m0, s72
	s_nop 0
	global_load_lds_dwordx4 v199, s[4:5]
	s_mov_b32 m0, s73
	v_exp_f32_e32 v134, v5
	v_add_f32_e32 v5, 0, v135
	v_add_f32_e32 v5, v136, v5
	v_add_f32_e32 v5, v137, v5
	v_add_f32_e32 v5, v138, v5
	v_add_f32_e32 v5, v10, v5
	s_waitcnt lgkmcnt(4)
	v_mfma_f32_32x32x16_bf16 v[96:111], v[250:253], v[172:175], v[96:111]
	ds_read_b128 v[250:253], v254 offset:49280
	v_add_f32_e32 v5, v11, v5
	v_add_f32_e32 v5, v12, v5
	v_add_f32_e32 v5, v13, v5
	v_add_f32_e32 v5, v14, v5
	v_add_f32_e32 v5, v15, v5
	v_add_f32_e32 v5, v18, v5
	v_add_f32_e32 v5, v19, v5
	v_add_f32_e32 v5, v20, v5
	s_waitcnt lgkmcnt(4)
	v_mfma_f32_32x32x16_bf16 v[112:127], v[234:237], v[168:171], v[112:127]
	ds_read_b128 v[234:237], v254 offset:57472
	v_add_f32_e32 v5, v21, v5
	v_add_f32_e32 v5, v22, v5
	v_add_f32_e32 v5, v23, v5
	v_add_f32_e32 v5, v7, v5
	v_add_f32_e32 v5, v24, v5
	v_add_f32_e32 v5, v25, v5
	v_add_f32_e32 v5, v26, v5
	s_waitcnt lgkmcnt(4)
	v_mfma_f32_32x32x16_bf16 v[96:111], v[238:241], v[168:171], v[96:111]
	s_addk_i32 s72, 0x400
	s_mov_b32 s73, m0
	s_mov_b32 m0, s72
	s_nop 0
	global_load_lds_dwordx4 v200, s[4:5]
	s_mov_b32 m0, s73
	v_add_f32_e32 v5, v27, v5
	v_add_f32_e32 v5, v28, v5
	v_add_f32_e32 v5, v29, v5
	v_add_f32_e32 v5, v30, v5
	v_add_f32_e32 v5, v31, v5
	v_add_f32_e32 v5, v128, v5
	v_add_f32_e32 v5, v129, v5
	v_add_f32_e32 v5, v130, v5
	s_waitcnt lgkmcnt(3)
	v_mfma_f32_32x32x16_bf16 v[112:127], v[242:245], v[164:167], v[112:127]
	v_add_f32_e32 v5, v131, v5
	v_add_f32_e32 v5, v132, v5
	v_add_f32_e32 v5, v133, v5
	v_add_f32_e32 v5, v134, v5
	v_mov_b32_e32 v6, v5
	v_cvt_pk_bf16_f32 v8, v135, v136
	v_cvt_pk_bf16_f32 v9, v137, v138
	v_cvt_pk_bf16_f32 v10, v10, v11
	s_waitcnt lgkmcnt(2)
	v_mfma_f32_32x32x16_bf16 v[96:111], v[246:249], v[164:167], v[96:111]
	s_nop 1
	v_permlane32_swap_b32_e32 v5, v6
	v_cvt_pk_bf16_f32 v11, v12, v13
	v_permlane32_swap_b32_e32 v8, v10
	v_cvt_pk_bf16_f32 v12, v14, v15
	v_cvt_pk_bf16_f32 v13, v18, v19
	v_cvt_pk_bf16_f32 v14, v20, v21
	v_cvt_pk_bf16_f32 v15, v22, v23
	s_waitcnt lgkmcnt(1)
	v_mfma_f32_32x32x16_bf16 v[112:127], v[250:253], v[160:163], v[112:127]
	v_cvt_pk_bf16_f32 v18, v7, v24
	v_cvt_pk_bf16_f32 v19, v25, v26
	v_cvt_pk_bf16_f32 v20, v27, v28
	v_cvt_pk_bf16_f32 v21, v29, v30
	v_cvt_pk_bf16_f32 v22, v31, v128
	v_cvt_pk_bf16_f32 v23, v129, v130
	v_cvt_pk_bf16_f32 v24, v131, v132
	s_waitcnt lgkmcnt(0)
	v_mfma_f32_32x32x16_bf16 v[96:111], v[234:237], v[160:163], v[96:111]
	v_cvt_pk_bf16_f32 v25, v133, v134
	v_permlane32_swap_b32_e32 v9, v11
	v_permlane32_swap_b32_e32 v12, v14
	v_permlane32_swap_b32_e32 v13, v15
	v_permlane32_swap_b32_e32 v18, v20
	v_permlane32_swap_b32_e32 v19, v21
	v_permlane32_swap_b32_e32 v22, v24
	v_permlane32_swap_b32_e32 v23, v25
	s_setprio 0
	v_add_u32_e32 v7, s77, v206
	ds_read_b64_tr_b16 v[26:27], v7 offset:0
	ds_read_b64_tr_b16 v[28:29], v7 offset:0x800
	ds_read_b64_tr_b16 v[128:129], v7 offset:0x1000
	ds_read_b64_tr_b16 v[130:131], v7 offset:0x1800
	ds_read_b64_tr_b16 v[132:133], v7 offset:0x2000
	ds_read_b64_tr_b16 v[134:135], v7 offset:0x2800
	ds_read_b64_tr_b16 v[136:137], v7 offset:0x3000
	ds_read_b64_tr_b16 v[138:139], v7 offset:0x3800
	s_waitcnt lgkmcnt(0)
	s_nop 0
	v_mfma_f32_32x32x16_bf16 v[32:47], v[8:11], v[26:29], v[32:47]
	ds_read_b64_tr_b16 v[26:27], v7 offset:0x200
	ds_read_b64_tr_b16 v[28:29], v7 offset:0xa00
	v_mfma_f32_32x32x16_bf16 v[32:47], v[12:15], v[128:131], v[32:47]
	ds_read_b64_tr_b16 v[128:129], v7 offset:0x1200
	ds_read_b64_tr_b16 v[130:131], v7 offset:0x1a00
	v_mfma_f32_32x32x16_bf16 v[32:47], v[18:21], v[132:135], v[32:47]
	ds_read_b64_tr_b16 v[132:133], v7 offset:0x2200
	ds_read_b64_tr_b16 v[134:135], v7 offset:0x2a00
	v_mfma_f32_32x32x16_bf16 v[32:47], v[22:25], v[136:139], v[32:47]
	ds_read_b64_tr_b16 v[136:137], v7 offset:0x3200
	ds_read_b64_tr_b16 v[138:139], v7 offset:0x3a00
	s_waitcnt lgkmcnt(0)
	v_mfma_f32_32x32x16_bf16 v[48:63], v[8:11], v[26:29], v[48:63]
	ds_read_b64_tr_b16 v[26:27], v7 offset:0x400
	ds_read_b64_tr_b16 v[28:29], v7 offset:0xc00
	v_mfma_f32_32x32x16_bf16 v[48:63], v[12:15], v[128:131], v[48:63]
	ds_read_b64_tr_b16 v[128:129], v7 offset:0x1400
	ds_read_b64_tr_b16 v[130:131], v7 offset:0x1c00
	v_mfma_f32_32x32x16_bf16 v[48:63], v[18:21], v[132:135], v[48:63]
	ds_read_b64_tr_b16 v[132:133], v7 offset:0x2400
	ds_read_b64_tr_b16 v[134:135], v7 offset:0x2c00
	v_mfma_f32_32x32x16_bf16 v[48:63], v[22:25], v[136:139], v[48:63]
	ds_read_b64_tr_b16 v[136:137], v7 offset:0x3400
	ds_read_b64_tr_b16 v[138:139], v7 offset:0x3c00
	s_waitcnt lgkmcnt(0)
	v_mfma_f32_32x32x16_bf16 v[64:79], v[8:11], v[26:29], v[64:79]
	ds_read_b64_tr_b16 v[26:27], v7 offset:0x600
	ds_read_b64_tr_b16 v[28:29], v7 offset:0xe00
	v_mfma_f32_32x32x16_bf16 v[64:79], v[12:15], v[128:131], v[64:79]
	ds_read_b64_tr_b16 v[128:129], v7 offset:0x1600
	ds_read_b64_tr_b16 v[130:131], v7 offset:0x1e00
	v_mfma_f32_32x32x16_bf16 v[64:79], v[18:21], v[132:135], v[64:79]
	ds_read_b64_tr_b16 v[132:133], v7 offset:0x2600
	ds_read_b64_tr_b16 v[134:135], v7 offset:0x2e00
	v_mfma_f32_32x32x16_bf16 v[64:79], v[22:25], v[136:139], v[64:79]
	ds_read_b64_tr_b16 v[136:137], v7 offset:0x3600
	ds_read_b64_tr_b16 v[138:139], v7 offset:0x3e00
	s_waitcnt lgkmcnt(0)
	v_mfma_f32_32x32x16_bf16 v[80:95], v[8:11], v[26:29], v[80:95]
	v_max_f32_e32 v7, v113, v113
	v_max_f32_e32 v8, v112, v112
	v_max_f32_e32 v7, v8, v7
	v_max3_f32 v7, v7, v114, v115
	v_max3_f32 v7, v7, v116, v117
	v_max3_f32 v7, v7, v118, v119
	v_max3_f32 v7, v7, v120, v121
	v_max3_f32 v7, v7, v122, v123
	v_max3_f32 v7, v7, v124, v125
	v_max3_f32 v7, v7, v126, v127
	v_mfma_f32_32x32x16_bf16 v[80:95], v[12:15], v[128:131], v[80:95]
	v_max3_f32 v7, v7, v96, v97
	v_max3_f32 v7, v7, v98, v99
	v_max3_f32 v7, v7, v100, v101
	v_max3_f32 v7, v7, v102, v103
	v_max3_f32 v7, v7, v104, v105
	v_max3_f32 v7, v7, v106, v107
	v_max3_f32 v7, v7, v108, v109
	v_max3_f32 v7, v7, v110, v111
	v_mfma_f32_32x32x16_bf16 v[80:95], v[18:21], v[132:135], v[80:95]
	v_mov_b32_e32 v8, v7
	s_nop 1
	v_permlane32_swap_b32_e32 v7, v8
	v_max_f32_e32 v8, v8, v8
	v_max_f32_e32 v7, v7, v7
	v_max_f32_e32 v7, v7, v8
	v_sub_f32_e32 v8, v7, v2
	v_mul_f32_e32 v8, 0x3db504f3, v8
	v_cmp_ge_f32_e32 vcc, s84, v8
	v_max_f32_e32 v8, v2, v2
	v_max_f32_e32 v8, v8, v7
	v_mfma_f32_32x32x16_bf16 v[80:95], v[22:25], v[136:139], v[80:95]
	v_sub_f32_e32 v7, v2, v8
	v_mul_f32_e32 v7, 0x3e0293ee, v7
	v_exp_f32_e32 v7, v7
	s_cmp_eq_u64 vcc, exec
	s_cselect_b64 s[4:5], -1, 0
	v_cndmask_b32_e64 v7, v7, 1.0, s[4:5]
	v_cmp_gt_f32_e32 vcc, 1.0, v7
	s_cbranch_vccz .LBB0_317
	s_and_saveexec_b64 s[72:73], s[2:3]
	ds_write_b32 v204, v7 offset:128
	s_or_b64 exec, exec, s[72:73]
	s_waitcnt lgkmcnt(0)
	ds_read_b128 v[10:13], v203 offset:224
	ds_read_b128 v[18:21], v203 offset:192
	ds_read_b128 v[22:25], v203 offset:160
	ds_read_b128 v[26:29], v203 offset:128
	s_waitcnt lgkmcnt(3)
	v_pk_mul_f32 v[46:47], v[46:47], v[12:13]
	s_waitcnt lgkmcnt(2)
	v_pk_mul_f32 v[42:43], v[42:43], v[20:21]
	s_waitcnt lgkmcnt(1)
	v_pk_mul_f32 v[38:39], v[38:39], v[24:25]
	s_waitcnt lgkmcnt(0)
	v_pk_mul_f32 v[34:35], v[34:35], v[28:29]
	v_pk_mul_f32 v[44:45], v[44:45], v[10:11]
	v_pk_mul_f32 v[40:41], v[40:41], v[18:19]
	v_pk_mul_f32 v[36:37], v[36:37], v[22:23]
	v_pk_mul_f32 v[32:33], v[32:33], v[26:27]
	v_pk_mul_f32 v[62:63], v[62:63], v[12:13]
	v_pk_mul_f32 v[58:59], v[58:59], v[20:21]
	v_pk_mul_f32 v[54:55], v[54:55], v[24:25]
	v_pk_mul_f32 v[50:51], v[50:51], v[28:29]
	v_pk_mul_f32 v[60:61], v[60:61], v[10:11]
	v_pk_mul_f32 v[56:57], v[56:57], v[18:19]
	v_pk_mul_f32 v[52:53], v[52:53], v[22:23]
	v_pk_mul_f32 v[48:49], v[48:49], v[26:27]
	v_pk_mul_f32 v[78:79], v[78:79], v[12:13]
	v_pk_mul_f32 v[74:75], v[74:75], v[20:21]
	v_pk_mul_f32 v[70:71], v[70:71], v[24:25]
	v_pk_mul_f32 v[66:67], v[66:67], v[28:29]
	v_pk_mul_f32 v[76:77], v[76:77], v[10:11]
	v_pk_mul_f32 v[72:73], v[72:73], v[18:19]
	v_pk_mul_f32 v[68:69], v[68:69], v[22:23]
	v_pk_mul_f32 v[64:65], v[64:65], v[26:27]
	v_pk_mul_f32 v[94:95], v[94:95], v[12:13]
	v_pk_mul_f32 v[90:91], v[90:91], v[20:21]
	v_pk_mul_f32 v[86:87], v[86:87], v[24:25]
	v_pk_mul_f32 v[82:83], v[82:83], v[28:29]
	v_pk_mul_f32 v[92:93], v[92:93], v[10:11]
	v_pk_mul_f32 v[88:89], v[88:89], v[18:19]
	v_pk_mul_f32 v[84:85], v[84:85], v[22:23]
	v_pk_mul_f32 v[80:81], v[80:81], v[26:27]

.LBB0_643:
	v_lshl_or_b32 v148, s58, 8, v151
	v_lshl_or_b32 v144, s60, 8, v152
	v_ashrrev_i32_e32 v149, 31, v148
	v_lshlrev_b64 v[168:169], 13, v[148:149]
	v_ashrrev_i32_e32 v145, 31, v144
	v_lshl_add_u64 v[160:161], s[52:53], 0, v[168:169]
	v_lshlrev_b64 v[146:147], 2, v[144:145]
	v_lshl_add_u64 v[170:171], v[160:161], 0, v[146:147]
	s_mov_b32 s98, 0x20000
	s_mov_b32 s99, 0
	s_mov_b32 s100, 0xa0000
	s_mov_b32 s101, 0
	global_load_dwordx4 v[184:187], v[170:171], off
	global_load_dwordx4 v[188:191], v[170:171], off offset:16
	global_load_dwordx4 v[192:195], v[170:171], off offset:512
	global_load_dwordx4 v[196:199], v[170:171], off offset:528
	v_lshl_add_u64 v[216:217], v[170:171], 0, s[98:99]
	global_load_dwordx4 v[200:203], v[216:217], off
	global_load_dwordx4 v[204:207], v[216:217], off offset:16
	global_load_dwordx4 v[208:211], v[216:217], off offset:512
	global_load_dwordx4 v[212:215], v[216:217], off offset:528
	v_lshlrev_b64 v[172:173], 12, v[148:149]
	v_lshl_add_u64 v[168:169], s[0:1], 0, v[168:169]
	v_lshl_add_u64 v[172:173], s[14:15], 0, v[172:173]
	v_lshl_add_u64 v[168:169], v[168:169], 0, v[146:147]
	v_lshl_add_u64 v[172:173], v[144:145], 1, v[172:173]
	s_waitcnt vmcnt(3)
	v_pk_add_f32 v[126:127], v[126:127], v[186:187]
	v_pk_add_f32 v[124:125], v[124:125], v[184:185]
	v_pk_add_f32 v[122:123], v[122:123], v[190:191]
	v_pk_add_f32 v[120:121], v[120:121], v[188:189]
	global_store_dwordx4 v[168:169], v[124:127], off
	global_store_dwordx4 v[168:169], v[120:123], off offset:16
	v_cvt_pk_bf16_f32 v160, v124, v125
	v_cvt_pk_bf16_f32 v161, v126, v127
	v_cvt_pk_bf16_f32 v162, v120, v121
	v_cvt_pk_bf16_f32 v163, v122, v123
	global_store_dwordx4 v[172:173], v[160:163], off
	s_nop 0
	v_mul_f32_e32 v125, v125, v125
	v_mul_f32_e32 v127, v127, v127
	v_mul_f32_e32 v121, v121, v121
	v_fmac_f32_e32 v125, v124, v124
	v_fmac_f32_e32 v127, v126, v126
	v_mul_f32_e32 v123, v123, v123
	v_fmac_f32_e32 v121, v120, v120
	v_add_f32_e32 v120, v125, v127
	v_fmac_f32_e32 v123, v122, v122
	v_add_f32_e32 v120, v120, v121
	v_add_f32_e32 v124, v123, v120
	v_pk_add_f32 v[118:119], v[118:119], v[194:195]
	v_pk_add_f32 v[116:117], v[116:117], v[192:193]
	v_pk_add_f32 v[120:121], v[112:113], v[196:197]
	v_mul_f32_e32 v112, v117, v117
	v_mul_f32_e32 v113, v119, v119
	v_pk_add_f32 v[122:123], v[114:115], v[198:199]
	v_lshl_add_u64 v[216:217], v[216:217], 0, s[98:99]
	global_load_dwordx4 v[184:187], v[216:217], off
	global_load_dwordx4 v[188:191], v[216:217], off offset:16
	global_load_dwordx4 v[192:195], v[216:217], off offset:512
	global_load_dwordx4 v[196:199], v[216:217], off offset:528
	v_mul_f32_e32 v114, v121, v121
	v_fmac_f32_e32 v112, v116, v116
	v_fmac_f32_e32 v113, v118, v118
	v_mul_f32_e32 v115, v123, v123
	v_fmac_f32_e32 v114, v120, v120
	v_add_f32_e32 v112, v112, v113
	v_add_f32_e32 v112, v112, v114
	v_fmac_f32_e32 v115, v122, v122
	v_add_f32_e32 v112, v115, v112
	v_add_f32_e32 v112, v124, v112
	ds_bpermute_b32 v113, v176, v112
	global_store_dwordx4 v[168:169], v[116:119], off offset:512
	global_store_dwordx4 v[168:169], v[120:123], off offset:528
	v_cvt_pk_bf16_f32 v114, v116, v117
	v_cvt_pk_bf16_f32 v115, v118, v119
	s_waitcnt lgkmcnt(0)
	v_add_f32_e32 v112, v112, v113
	ds_bpermute_b32 v113, v177, v112
	v_cvt_pk_bf16_f32 v116, v120, v121
	v_cvt_pk_bf16_f32 v117, v122, v123
	global_store_dwordx4 v[172:173], v[114:117], off offset:256
	s_and_saveexec_b64 s[58:59], s[6:7]
	s_cbranch_execz .LBB0_645
	v_lshl_add_u64 v[114:115], v[148:149], 2, s[16:17]
	s_waitcnt lgkmcnt(0)
	v_add_f32_e32 v112, v112, v113
	global_atomic_add_f32 v[114:115], v112, off
.LBB0_645:
	s_or_b64 exec, exec, s[58:59]
	v_or_b32_e32 v112, 16, v148
	s_waitcnt lgkmcnt(0)
	v_ashrrev_i32_e32 v113, 31, v112
	v_lshlrev_b64 v[122:123], 13, v[112:113]
	v_lshl_add_u64 v[114:115], s[52:53], 0, v[122:123]
	v_lshl_add_u64 v[124:125], v[114:115], 0, v[146:147]
	v_lshlrev_b64 v[126:127], 12, v[112:113]
	v_lshl_add_u64 v[122:123], s[0:1], 0, v[122:123]
	v_lshl_add_u64 v[126:127], s[14:15], 0, v[126:127]
	v_lshl_add_u64 v[122:123], v[122:123], 0, v[146:147]
	v_lshl_add_u64 v[126:127], v[144:145], 1, v[126:127]
	s_waitcnt vmcnt(10)
	v_pk_add_f32 v[110:111], v[110:111], v[202:203]
	v_pk_add_f32 v[108:109], v[108:109], v[200:201]
	v_pk_add_f32 v[106:107], v[106:107], v[206:207]
	v_pk_add_f32 v[104:105], v[104:105], v[204:205]
	global_store_dwordx4 v[122:123], v[108:111], off
	global_store_dwordx4 v[122:123], v[104:107], off offset:16
	v_cvt_pk_bf16_f32 v114, v108, v109
	v_cvt_pk_bf16_f32 v115, v110, v111
	v_cvt_pk_bf16_f32 v116, v104, v105
	v_cvt_pk_bf16_f32 v117, v106, v107
	global_store_dwordx4 v[126:127], v[114:117], off
	s_nop 0
	v_mul_f32_e32 v109, v109, v109
	v_mul_f32_e32 v111, v111, v111
	v_mul_f32_e32 v105, v105, v105
	v_fmac_f32_e32 v109, v108, v108
	v_fmac_f32_e32 v111, v110, v110
	v_mul_f32_e32 v107, v107, v107
	v_fmac_f32_e32 v105, v104, v104
	v_add_f32_e32 v104, v109, v111
	v_fmac_f32_e32 v107, v106, v106
	v_add_f32_e32 v104, v104, v105
	v_add_f32_e32 v108, v107, v104
	v_pk_add_f32 v[102:103], v[102:103], v[210:211]
	v_pk_add_f32 v[100:101], v[100:101], v[208:209]
	v_pk_add_f32 v[104:105], v[96:97], v[212:213]
	v_mul_f32_e32 v96, v101, v101
	v_mul_f32_e32 v97, v103, v103
	v_pk_add_f32 v[106:107], v[98:99], v[214:215]
	v_lshl_add_u64 v[216:217], v[216:217], 0, s[98:99]
	global_load_dwordx4 v[200:203], v[216:217], off
	global_load_dwordx4 v[204:207], v[216:217], off offset:16
	global_load_dwordx4 v[208:211], v[216:217], off offset:512
	global_load_dwordx4 v[212:215], v[216:217], off offset:528
	v_mul_f32_e32 v98, v105, v105
	v_fmac_f32_e32 v96, v100, v100
	v_fmac_f32_e32 v97, v102, v102
	v_mul_f32_e32 v99, v107, v107
	v_fmac_f32_e32 v98, v104, v104
	v_add_f32_e32 v96, v96, v97
	v_add_f32_e32 v96, v96, v98
	v_fmac_f32_e32 v99, v106, v106
	v_add_f32_e32 v96, v99, v96
	v_add_f32_e32 v96, v108, v96
	ds_bpermute_b32 v97, v176, v96
	global_store_dwordx4 v[122:123], v[100:103], off offset:512
	global_store_dwordx4 v[122:123], v[104:107], off offset:528
	v_cvt_pk_bf16_f32 v98, v100, v101
	v_cvt_pk_bf16_f32 v99, v102, v103
	s_waitcnt lgkmcnt(0)
	v_add_f32_e32 v96, v96, v97
	ds_bpermute_b32 v97, v177, v96
	v_cvt_pk_bf16_f32 v100, v104, v105
	v_cvt_pk_bf16_f32 v101, v106, v107
	global_store_dwordx4 v[126:127], v[98:101], off offset:256
	s_and_saveexec_b64 s[58:59], s[6:7]
	s_cbranch_execz .LBB0_647
	v_lshl_add_u64 v[98:99], v[112:113], 2, s[16:17]
	s_waitcnt lgkmcnt(0)
	v_add_f32_e32 v96, v96, v97
	global_atomic_add_f32 v[98:99], v96, off
.LBB0_647:
	s_or_b64 exec, exec, s[58:59]
	v_or_b32_e32 v96, 32, v148
	s_waitcnt lgkmcnt(0)
	v_ashrrev_i32_e32 v97, 31, v96
	v_lshlrev_b64 v[106:107], 13, v[96:97]
	v_lshl_add_u64 v[98:99], s[52:53], 0, v[106:107]
	v_lshl_add_u64 v[108:109], v[98:99], 0, v[146:147]
	v_lshlrev_b64 v[110:111], 12, v[96:97]
	v_lshl_add_u64 v[106:107], s[0:1], 0, v[106:107]
	v_lshl_add_u64 v[110:111], s[14:15], 0, v[110:111]
	v_lshl_add_u64 v[106:107], v[106:107], 0, v[146:147]
	v_lshl_add_u64 v[110:111], v[144:145], 1, v[110:111]
	s_waitcnt vmcnt(14)
	v_pk_add_f32 v[94:95], v[94:95], v[186:187]
	v_pk_add_f32 v[92:93], v[92:93], v[184:185]
	v_pk_add_f32 v[90:91], v[90:91], v[190:191]
	v_pk_add_f32 v[88:89], v[88:89], v[188:189]
	global_store_dwordx4 v[106:107], v[92:95], off
	global_store_dwordx4 v[106:107], v[88:91], off offset:16
	v_cvt_pk_bf16_f32 v98, v92, v93
	v_cvt_pk_bf16_f32 v99, v94, v95
	v_cvt_pk_bf16_f32 v100, v88, v89
	v_cvt_pk_bf16_f32 v101, v90, v91
	global_store_dwordx4 v[110:111], v[98:101], off
	s_nop 0
	v_mul_f32_e32 v93, v93, v93
	v_mul_f32_e32 v95, v95, v95
	v_mul_f32_e32 v89, v89, v89
	v_fmac_f32_e32 v93, v92, v92
	v_fmac_f32_e32 v95, v94, v94
	v_mul_f32_e32 v91, v91, v91
	v_fmac_f32_e32 v89, v88, v88
	v_add_f32_e32 v88, v93, v95
	v_fmac_f32_e32 v91, v90, v90
	v_add_f32_e32 v88, v88, v89
	v_add_f32_e32 v92, v91, v88
	v_pk_add_f32 v[86:87], v[86:87], v[194:195]
	v_pk_add_f32 v[84:85], v[84:85], v[192:193]
	v_pk_add_f32 v[88:89], v[80:81], v[196:197]
	v_mul_f32_e32 v80, v85, v85
	v_mul_f32_e32 v81, v87, v87
	v_pk_add_f32 v[90:91], v[82:83], v[198:199]
	v_lshl_add_u64 v[216:217], v[216:217], 0, s[100:101]
	global_load_dwordx4 v[184:187], v[216:217], off
	global_load_dwordx4 v[188:191], v[216:217], off offset:16
	global_load_dwordx4 v[192:195], v[216:217], off offset:512
	global_load_dwordx4 v[196:199], v[216:217], off offset:528
	v_mul_f32_e32 v82, v89, v89
	v_fmac_f32_e32 v80, v84, v84
	v_fmac_f32_e32 v81, v86, v86
	v_mul_f32_e32 v83, v91, v91
	v_fmac_f32_e32 v82, v88, v88
	v_add_f32_e32 v80, v80, v81
	v_add_f32_e32 v80, v80, v82
	v_fmac_f32_e32 v83, v90, v90
	v_add_f32_e32 v80, v83, v80
	v_add_f32_e32 v80, v92, v80
	ds_bpermute_b32 v81, v176, v80
	global_store_dwordx4 v[106:107], v[84:87], off offset:512
	global_store_dwordx4 v[106:107], v[88:91], off offset:528
	v_cvt_pk_bf16_f32 v82, v84, v85
	v_cvt_pk_bf16_f32 v83, v86, v87
	s_waitcnt lgkmcnt(0)
	v_add_f32_e32 v80, v80, v81
	ds_bpermute_b32 v81, v177, v80
	v_cvt_pk_bf16_f32 v84, v88, v89
	v_cvt_pk_bf16_f32 v85, v90, v91
	global_store_dwordx4 v[110:111], v[82:85], off offset:256
	s_and_saveexec_b64 s[58:59], s[6:7]
	s_cbranch_execz .LBB0_649
	v_lshl_add_u64 v[82:83], v[96:97], 2, s[16:17]
	s_waitcnt lgkmcnt(0)
	v_add_f32_e32 v80, v80, v81
	global_atomic_add_f32 v[82:83], v80, off
.LBB0_649:
	s_or_b64 exec, exec, s[58:59]
	v_or_b32_e32 v80, 48, v148
	s_waitcnt lgkmcnt(0)
	v_ashrrev_i32_e32 v81, 31, v80
	v_lshlrev_b64 v[90:91], 13, v[80:81]
	v_lshl_add_u64 v[82:83], s[52:53], 0, v[90:91]
	v_lshl_add_u64 v[92:93], v[82:83], 0, v[146:147]
	v_lshlrev_b64 v[94:95], 12, v[80:81]
	v_lshl_add_u64 v[90:91], s[0:1], 0, v[90:91]
	v_lshl_add_u64 v[94:95], s[14:15], 0, v[94:95]
	v_lshl_add_u64 v[90:91], v[90:91], 0, v[146:147]
	v_lshl_add_u64 v[94:95], v[144:145], 1, v[94:95]
	s_waitcnt vmcnt(14)
	v_pk_add_f32 v[78:79], v[78:79], v[202:203]
	v_pk_add_f32 v[76:77], v[76:77], v[200:201]
	v_pk_add_f32 v[74:75], v[74:75], v[206:207]
	v_pk_add_f32 v[72:73], v[72:73], v[204:205]
	global_store_dwordx4 v[90:91], v[76:79], off
	global_store_dwordx4 v[90:91], v[72:75], off offset:16
	v_cvt_pk_bf16_f32 v82, v76, v77
	v_cvt_pk_bf16_f32 v83, v78, v79
	v_cvt_pk_bf16_f32 v84, v72, v73
	v_cvt_pk_bf16_f32 v85, v74, v75
	global_store_dwordx4 v[94:95], v[82:85], off
	s_nop 0
	v_mul_f32_e32 v77, v77, v77
	v_mul_f32_e32 v79, v79, v79
	v_mul_f32_e32 v73, v73, v73
	v_fmac_f32_e32 v77, v76, v76
	v_fmac_f32_e32 v79, v78, v78
	v_mul_f32_e32 v75, v75, v75
	v_fmac_f32_e32 v73, v72, v72
	v_add_f32_e32 v72, v77, v79
	v_fmac_f32_e32 v75, v74, v74
	v_add_f32_e32 v72, v72, v73
	v_add_f32_e32 v76, v75, v72
	v_pk_add_f32 v[70:71], v[70:71], v[210:211]
	v_pk_add_f32 v[68:69], v[68:69], v[208:209]
	v_pk_add_f32 v[72:73], v[64:65], v[212:213]
	v_mul_f32_e32 v64, v69, v69
	v_mul_f32_e32 v65, v71, v71
	v_pk_add_f32 v[74:75], v[66:67], v[214:215]
	v_lshl_add_u64 v[216:217], v[216:217], 0, s[98:99]
	global_load_dwordx4 v[200:203], v[216:217], off
	global_load_dwordx4 v[204:207], v[216:217], off offset:16
	global_load_dwordx4 v[208:211], v[216:217], off offset:512
	global_load_dwordx4 v[212:215], v[216:217], off offset:528
	v_mul_f32_e32 v66, v73, v73
	v_fmac_f32_e32 v64, v68, v68
	v_fmac_f32_e32 v65, v70, v70
	v_mul_f32_e32 v67, v75, v75
	v_fmac_f32_e32 v66, v72, v72
	v_add_f32_e32 v64, v64, v65
	v_add_f32_e32 v64, v64, v66
	v_fmac_f32_e32 v67, v74, v74
	v_add_f32_e32 v64, v67, v64
	v_add_f32_e32 v64, v76, v64
	ds_bpermute_b32 v65, v176, v64
	global_store_dwordx4 v[90:91], v[68:71], off offset:512
	global_store_dwordx4 v[90:91], v[72:75], off offset:528
	v_cvt_pk_bf16_f32 v66, v68, v69
	v_cvt_pk_bf16_f32 v67, v70, v71
	s_waitcnt lgkmcnt(0)
	v_add_f32_e32 v64, v64, v65
	ds_bpermute_b32 v65, v177, v64
	v_cvt_pk_bf16_f32 v68, v72, v73
	v_cvt_pk_bf16_f32 v69, v74, v75
	global_store_dwordx4 v[94:95], v[66:69], off offset:256
	s_and_saveexec_b64 s[58:59], s[6:7]
	s_cbranch_execz .LBB0_651
	v_lshl_add_u64 v[66:67], v[80:81], 2, s[16:17]
	s_waitcnt lgkmcnt(0)
	v_add_f32_e32 v64, v64, v65
	global_atomic_add_f32 v[66:67], v64, off
.LBB0_651:
	s_or_b64 exec, exec, s[58:59]
	v_or_b32_e32 v64, 0x80, v148
	s_waitcnt lgkmcnt(0)
	v_ashrrev_i32_e32 v65, 31, v64
	v_lshlrev_b64 v[74:75], 13, v[64:65]
	v_lshl_add_u64 v[66:67], s[52:53], 0, v[74:75]
	v_lshl_add_u64 v[76:77], v[66:67], 0, v[146:147]
	v_lshlrev_b64 v[78:79], 12, v[64:65]
	v_lshl_add_u64 v[74:75], s[0:1], 0, v[74:75]
	v_lshl_add_u64 v[78:79], s[14:15], 0, v[78:79]
	v_lshl_add_u64 v[74:75], v[74:75], 0, v[146:147]
	v_lshl_add_u64 v[78:79], v[144:145], 1, v[78:79]
	s_waitcnt vmcnt(14)
	v_pk_add_f32 v[62:63], v[62:63], v[186:187]
	v_pk_add_f32 v[60:61], v[60:61], v[184:185]
	v_pk_add_f32 v[58:59], v[58:59], v[190:191]
	v_pk_add_f32 v[56:57], v[56:57], v[188:189]
	global_store_dwordx4 v[74:75], v[60:63], off
	global_store_dwordx4 v[74:75], v[56:59], off offset:16
	v_cvt_pk_bf16_f32 v66, v60, v61
	v_cvt_pk_bf16_f32 v67, v62, v63
	v_cvt_pk_bf16_f32 v68, v56, v57
	v_cvt_pk_bf16_f32 v69, v58, v59
	global_store_dwordx4 v[78:79], v[66:69], off
	s_nop 0
	v_mul_f32_e32 v61, v61, v61
	v_mul_f32_e32 v63, v63, v63
	v_mul_f32_e32 v57, v57, v57
	v_fmac_f32_e32 v61, v60, v60
	v_fmac_f32_e32 v63, v62, v62
	v_mul_f32_e32 v59, v59, v59
	v_fmac_f32_e32 v57, v56, v56
	v_add_f32_e32 v56, v61, v63
	v_fmac_f32_e32 v59, v58, v58
	v_add_f32_e32 v56, v56, v57
	v_add_f32_e32 v60, v59, v56
	v_pk_add_f32 v[54:55], v[54:55], v[194:195]
	v_pk_add_f32 v[52:53], v[52:53], v[192:193]
	v_pk_add_f32 v[56:57], v[48:49], v[196:197]
	v_mul_f32_e32 v48, v53, v53
	v_mul_f32_e32 v49, v55, v55
	v_pk_add_f32 v[58:59], v[50:51], v[198:199]
	v_lshl_add_u64 v[216:217], v[216:217], 0, s[98:99]
	global_load_dwordx4 v[184:187], v[216:217], off
	global_load_dwordx4 v[188:191], v[216:217], off offset:16
	global_load_dwordx4 v[192:195], v[216:217], off offset:512
	global_load_dwordx4 v[196:199], v[216:217], off offset:528
	v_mul_f32_e32 v50, v57, v57
	v_fmac_f32_e32 v48, v52, v52
	v_fmac_f32_e32 v49, v54, v54
	v_mul_f32_e32 v51, v59, v59
	v_fmac_f32_e32 v50, v56, v56
	v_add_f32_e32 v48, v48, v49
	v_add_f32_e32 v48, v48, v50
	v_fmac_f32_e32 v51, v58, v58
	v_add_f32_e32 v48, v51, v48
	v_add_f32_e32 v48, v60, v48
	ds_bpermute_b32 v49, v176, v48
	global_store_dwordx4 v[74:75], v[52:55], off offset:512
	global_store_dwordx4 v[74:75], v[56:59], off offset:528
	v_cvt_pk_bf16_f32 v50, v52, v53
	v_cvt_pk_bf16_f32 v51, v54, v55
	s_waitcnt lgkmcnt(0)
	v_add_f32_e32 v48, v48, v49
	ds_bpermute_b32 v49, v177, v48
	v_cvt_pk_bf16_f32 v52, v56, v57
	v_cvt_pk_bf16_f32 v53, v58, v59
	global_store_dwordx4 v[78:79], v[50:53], off offset:256
	s_and_saveexec_b64 s[58:59], s[6:7]
	s_cbranch_execz .LBB0_653
	v_lshl_add_u64 v[50:51], v[64:65], 2, s[16:17]
	s_waitcnt lgkmcnt(0)
	v_add_f32_e32 v48, v48, v49
	global_atomic_add_f32 v[50:51], v48, off
.LBB0_653:
	s_or_b64 exec, exec, s[58:59]
	v_or_b32_e32 v48, 0x90, v148
	s_waitcnt lgkmcnt(0)
	v_ashrrev_i32_e32 v49, 31, v48
	v_lshlrev_b64 v[58:59], 13, v[48:49]
	v_lshl_add_u64 v[50:51], s[52:53], 0, v[58:59]
	v_lshl_add_u64 v[60:61], v[50:51], 0, v[146:147]
	v_lshlrev_b64 v[62:63], 12, v[48:49]
	v_lshl_add_u64 v[58:59], s[0:1], 0, v[58:59]
	v_lshl_add_u64 v[62:63], s[14:15], 0, v[62:63]
	v_lshl_add_u64 v[58:59], v[58:59], 0, v[146:147]
	v_lshl_add_u64 v[62:63], v[144:145], 1, v[62:63]
	s_waitcnt vmcnt(14)
	v_pk_add_f32 v[46:47], v[46:47], v[202:203]
	v_pk_add_f32 v[44:45], v[44:45], v[200:201]
	v_pk_add_f32 v[42:43], v[42:43], v[206:207]
	v_pk_add_f32 v[40:41], v[40:41], v[204:205]
	global_store_dwordx4 v[58:59], v[44:47], off
	global_store_dwordx4 v[58:59], v[40:43], off offset:16
	v_cvt_pk_bf16_f32 v50, v44, v45
	v_cvt_pk_bf16_f32 v51, v46, v47
	v_cvt_pk_bf16_f32 v52, v40, v41
	v_cvt_pk_bf16_f32 v53, v42, v43
	global_store_dwordx4 v[62:63], v[50:53], off
	s_nop 0
	v_mul_f32_e32 v45, v45, v45
	v_mul_f32_e32 v47, v47, v47
	v_mul_f32_e32 v41, v41, v41
	v_fmac_f32_e32 v45, v44, v44
	v_fmac_f32_e32 v47, v46, v46
	v_mul_f32_e32 v43, v43, v43
	v_fmac_f32_e32 v41, v40, v40
	v_add_f32_e32 v40, v45, v47
	v_fmac_f32_e32 v43, v42, v42
	v_add_f32_e32 v40, v40, v41
	v_add_f32_e32 v44, v43, v40
	v_pk_add_f32 v[38:39], v[38:39], v[210:211]
	v_pk_add_f32 v[36:37], v[36:37], v[208:209]
	v_pk_add_f32 v[40:41], v[32:33], v[212:213]
	v_mul_f32_e32 v32, v37, v37
	v_mul_f32_e32 v33, v39, v39
	v_pk_add_f32 v[42:43], v[34:35], v[214:215]
	v_lshl_add_u64 v[216:217], v[216:217], 0, s[98:99]
	global_load_dwordx4 v[200:203], v[216:217], off
	global_load_dwordx4 v[204:207], v[216:217], off offset:16
	global_load_dwordx4 v[208:211], v[216:217], off offset:512
	global_load_dwordx4 v[212:215], v[216:217], off offset:528
	v_mul_f32_e32 v34, v41, v41
	v_fmac_f32_e32 v32, v36, v36
	v_fmac_f32_e32 v33, v38, v38
	v_mul_f32_e32 v35, v43, v43
	v_fmac_f32_e32 v34, v40, v40
	v_add_f32_e32 v32, v32, v33
	v_add_f32_e32 v32, v32, v34
	v_fmac_f32_e32 v35, v42, v42
	v_add_f32_e32 v32, v35, v32
	v_add_f32_e32 v32, v44, v32
	ds_bpermute_b32 v33, v176, v32
	global_store_dwordx4 v[58:59], v[36:39], off offset:512
	global_store_dwordx4 v[58:59], v[40:43], off offset:528
	v_cvt_pk_bf16_f32 v34, v36, v37
	v_cvt_pk_bf16_f32 v35, v38, v39
	s_waitcnt lgkmcnt(0)
	v_add_f32_e32 v32, v32, v33
	ds_bpermute_b32 v33, v177, v32
	v_cvt_pk_bf16_f32 v36, v40, v41
	v_cvt_pk_bf16_f32 v37, v42, v43
	global_store_dwordx4 v[62:63], v[34:37], off offset:256
	s_and_saveexec_b64 s[58:59], s[6:7]
	s_cbranch_execz .LBB0_655
	v_lshl_add_u64 v[34:35], v[48:49], 2, s[16:17]
	s_waitcnt lgkmcnt(0)
	v_add_f32_e32 v32, v32, v33
	global_atomic_add_f32 v[34:35], v32, off
.LBB0_655:
	s_or_b64 exec, exec, s[58:59]
	v_or_b32_e32 v32, 0xa0, v148
	s_waitcnt lgkmcnt(0)
	v_ashrrev_i32_e32 v33, 31, v32
	v_lshlrev_b64 v[42:43], 13, v[32:33]
	v_lshl_add_u64 v[34:35], s[52:53], 0, v[42:43]
	v_lshl_add_u64 v[44:45], v[34:35], 0, v[146:147]
	v_lshlrev_b64 v[46:47], 12, v[32:33]
	v_lshl_add_u64 v[42:43], s[0:1], 0, v[42:43]
	v_lshl_add_u64 v[46:47], s[14:15], 0, v[46:47]
	v_lshl_add_u64 v[42:43], v[42:43], 0, v[146:147]
	v_lshl_add_u64 v[46:47], v[144:145], 1, v[46:47]
	s_waitcnt vmcnt(14)
	v_pk_add_f32 v[30:31], v[30:31], v[186:187]
	v_pk_add_f32 v[28:29], v[28:29], v[184:185]
	v_pk_add_f32 v[26:27], v[26:27], v[190:191]
	v_pk_add_f32 v[24:25], v[24:25], v[188:189]
	global_store_dwordx4 v[42:43], v[28:31], off
	global_store_dwordx4 v[42:43], v[24:27], off offset:16
	v_cvt_pk_bf16_f32 v34, v28, v29
	v_cvt_pk_bf16_f32 v35, v30, v31
	v_cvt_pk_bf16_f32 v36, v24, v25
	v_cvt_pk_bf16_f32 v37, v26, v27
	global_store_dwordx4 v[46:47], v[34:37], off
	s_nop 0
	v_mul_f32_e32 v29, v29, v29
	v_mul_f32_e32 v31, v31, v31
	v_mul_f32_e32 v25, v25, v25
	v_fmac_f32_e32 v29, v28, v28
	v_fmac_f32_e32 v31, v30, v30
	v_mul_f32_e32 v27, v27, v27
	v_fmac_f32_e32 v25, v24, v24
	v_add_f32_e32 v24, v29, v31
	v_fmac_f32_e32 v27, v26, v26
	v_add_f32_e32 v24, v24, v25
	v_add_f32_e32 v28, v27, v24
	v_pk_add_f32 v[22:23], v[22:23], v[194:195]
	v_pk_add_f32 v[20:21], v[20:21], v[192:193]
	v_pk_add_f32 v[24:25], v[16:17], v[196:197]
	v_mul_f32_e32 v16, v21, v21
	v_mul_f32_e32 v17, v23, v23
	v_pk_add_f32 v[26:27], v[18:19], v[198:199]
	v_mul_f32_e32 v18, v25, v25
	v_fmac_f32_e32 v16, v20, v20
	v_fmac_f32_e32 v17, v22, v22
	v_mul_f32_e32 v19, v27, v27
	v_fmac_f32_e32 v18, v24, v24
	v_add_f32_e32 v16, v16, v17
	v_add_f32_e32 v16, v16, v18
	v_fmac_f32_e32 v19, v26, v26
	v_add_f32_e32 v16, v19, v16
	v_add_f32_e32 v16, v28, v16
	ds_bpermute_b32 v17, v176, v16
	global_store_dwordx4 v[42:43], v[20:23], off offset:512
	global_store_dwordx4 v[42:43], v[24:27], off offset:528
	v_cvt_pk_bf16_f32 v18, v20, v21
	v_cvt_pk_bf16_f32 v19, v22, v23
	s_waitcnt lgkmcnt(0)
	v_add_f32_e32 v16, v16, v17
	ds_bpermute_b32 v17, v177, v16
	v_cvt_pk_bf16_f32 v20, v24, v25
	v_cvt_pk_bf16_f32 v21, v26, v27
	global_store_dwordx4 v[46:47], v[18:21], off offset:256
	s_and_saveexec_b64 s[58:59], s[6:7]
	s_cbranch_execz .LBB0_657
	v_lshl_add_u64 v[18:19], v[32:33], 2, s[16:17]
	s_waitcnt lgkmcnt(0)
	v_add_f32_e32 v16, v16, v17
	global_atomic_add_f32 v[18:19], v16, off
.LBB0_657:
	s_or_b64 exec, exec, s[58:59]
	v_or_b32_e32 v16, 0xb0, v148
	s_waitcnt lgkmcnt(0)
	v_ashrrev_i32_e32 v17, 31, v16
	v_lshlrev_b64 v[26:27], 13, v[16:17]
	v_lshl_add_u64 v[18:19], s[52:53], 0, v[26:27]
	v_lshl_add_u64 v[28:29], v[18:19], 0, v[146:147]
	v_lshlrev_b64 v[30:31], 12, v[16:17]
	v_lshl_add_u64 v[26:27], s[0:1], 0, v[26:27]
	v_lshl_add_u64 v[30:31], s[14:15], 0, v[30:31]
	v_lshl_add_u64 v[26:27], v[26:27], 0, v[146:147]
	v_lshl_add_u64 v[30:31], v[144:145], 1, v[30:31]
	s_waitcnt vmcnt(10)
	v_pk_add_f32 v[14:15], v[14:15], v[202:203]
	v_pk_add_f32 v[12:13], v[12:13], v[200:201]
	v_pk_add_f32 v[10:11], v[10:11], v[206:207]
	v_pk_add_f32 v[8:9], v[8:9], v[204:205]
	global_store_dwordx4 v[26:27], v[12:15], off
	global_store_dwordx4 v[26:27], v[8:11], off offset:16
	v_cvt_pk_bf16_f32 v18, v12, v13
	v_cvt_pk_bf16_f32 v19, v14, v15
	v_cvt_pk_bf16_f32 v20, v8, v9
	v_cvt_pk_bf16_f32 v21, v10, v11
	global_store_dwordx4 v[30:31], v[18:21], off
	s_nop 0
	v_mul_f32_e32 v13, v13, v13
	v_mul_f32_e32 v15, v15, v15
	v_mul_f32_e32 v9, v9, v9
	v_fmac_f32_e32 v13, v12, v12
	v_fmac_f32_e32 v15, v14, v14
	v_mul_f32_e32 v11, v11, v11
	v_fmac_f32_e32 v9, v8, v8
	v_add_f32_e32 v8, v13, v15
	v_fmac_f32_e32 v11, v10, v10
	v_add_f32_e32 v8, v8, v9
	v_add_f32_e32 v12, v11, v8
	v_pk_add_f32 v[6:7], v[6:7], v[210:211]
	v_pk_add_f32 v[4:5], v[4:5], v[208:209]
	v_pk_add_f32 v[8:9], v[0:1], v[212:213]
	v_mul_f32_e32 v0, v5, v5
	v_mul_f32_e32 v1, v7, v7
	v_pk_add_f32 v[10:11], v[2:3], v[214:215]
	v_mul_f32_e32 v2, v9, v9
	v_fmac_f32_e32 v0, v4, v4
	v_fmac_f32_e32 v1, v6, v6
	v_mul_f32_e32 v3, v11, v11
	v_fmac_f32_e32 v2, v8, v8
	v_add_f32_e32 v0, v0, v1
	v_add_f32_e32 v0, v0, v2
	v_fmac_f32_e32 v3, v10, v10
	v_add_f32_e32 v0, v3, v0
	v_add_f32_e32 v0, v12, v0
	ds_bpermute_b32 v1, v176, v0
	global_store_dwordx4 v[26:27], v[4:7], off offset:512
	global_store_dwordx4 v[26:27], v[8:11], off offset:528
	v_cvt_pk_bf16_f32 v2, v4, v5
	v_cvt_pk_bf16_f32 v3, v6, v7
	s_waitcnt lgkmcnt(0)
	v_add_f32_e32 v0, v0, v1
	ds_bpermute_b32 v1, v177, v0
	v_cvt_pk_bf16_f32 v4, v8, v9
	v_cvt_pk_bf16_f32 v5, v10, v11
	global_store_dwordx4 v[30:31], v[2:5], off offset:256
	s_and_saveexec_b64 s[58:59], s[6:7]
	s_cbranch_execz .LBB0_659
	v_lshl_add_u64 v[2:3], v[16:17], 2, s[16:17]
	s_waitcnt lgkmcnt(0)
	v_add_f32_e32 v0, v0, v1
	global_atomic_add_f32 v[2:3], v0, off

.LBB0_813:
	v_lshl_or_b32 v148, s60, 8, v151
	v_lshl_or_b32 v144, s62, 8, v152
	v_ashrrev_i32_e32 v149, 31, v148
	v_lshlrev_b64 v[168:169], 13, v[148:149]
	v_ashrrev_i32_e32 v145, 31, v144
	v_lshl_add_u64 v[160:161], s[0:1], 0, v[168:169]
	v_lshlrev_b64 v[146:147], 2, v[144:145]
	v_lshl_add_u64 v[170:171], v[160:161], 0, v[146:147]
	s_mov_b32 s98, 0x20000
	s_mov_b32 s99, 0
	s_mov_b32 s100, 0xa0000
	s_mov_b32 s101, 0
	global_load_dwordx4 v[184:187], v[170:171], off
	global_load_dwordx4 v[188:191], v[170:171], off offset:16
	global_load_dwordx4 v[192:195], v[170:171], off offset:512
	global_load_dwordx4 v[196:199], v[170:171], off offset:528
	v_lshl_add_u64 v[216:217], v[170:171], 0, s[98:99]
	global_load_dwordx4 v[200:203], v[216:217], off
	global_load_dwordx4 v[204:207], v[216:217], off offset:16
	global_load_dwordx4 v[208:211], v[216:217], off offset:512
	global_load_dwordx4 v[212:215], v[216:217], off offset:528
	v_lshlrev_b64 v[172:173], 12, v[148:149]
	v_lshl_add_u64 v[168:169], s[10:11], 0, v[168:169]
	v_lshl_add_u64 v[172:173], s[16:17], 0, v[172:173]
	v_lshl_add_u64 v[168:169], v[168:169], 0, v[146:147]
	v_lshl_add_u64 v[172:173], v[144:145], 1, v[172:173]
	s_waitcnt vmcnt(3)
	v_pk_add_f32 v[126:127], v[126:127], v[186:187]
	v_pk_add_f32 v[124:125], v[124:125], v[184:185]
	v_pk_add_f32 v[122:123], v[122:123], v[190:191]
	v_pk_add_f32 v[120:121], v[120:121], v[188:189]
	global_store_dwordx4 v[168:169], v[124:127], off
	global_store_dwordx4 v[168:169], v[120:123], off offset:16
	v_cvt_pk_bf16_f32 v160, v124, v125
	v_cvt_pk_bf16_f32 v161, v126, v127
	v_cvt_pk_bf16_f32 v162, v120, v121
	v_cvt_pk_bf16_f32 v163, v122, v123
	global_store_dwordx4 v[172:173], v[160:163], off
	s_nop 0
	v_mul_f32_e32 v125, v125, v125
	v_mul_f32_e32 v127, v127, v127
	v_mul_f32_e32 v121, v121, v121
	v_fmac_f32_e32 v125, v124, v124
	v_fmac_f32_e32 v127, v126, v126
	v_mul_f32_e32 v123, v123, v123
	v_fmac_f32_e32 v121, v120, v120
	v_add_f32_e32 v120, v125, v127
	v_fmac_f32_e32 v123, v122, v122
	v_add_f32_e32 v120, v120, v121
	v_add_f32_e32 v124, v123, v120
	v_pk_add_f32 v[118:119], v[118:119], v[194:195]
	v_pk_add_f32 v[116:117], v[116:117], v[192:193]
	v_pk_add_f32 v[120:121], v[112:113], v[196:197]
	v_mul_f32_e32 v112, v117, v117
	v_mul_f32_e32 v113, v119, v119
	v_pk_add_f32 v[122:123], v[114:115], v[198:199]
	v_lshl_add_u64 v[216:217], v[216:217], 0, s[98:99]
	global_load_dwordx4 v[184:187], v[216:217], off
	global_load_dwordx4 v[188:191], v[216:217], off offset:16
	global_load_dwordx4 v[192:195], v[216:217], off offset:512
	global_load_dwordx4 v[196:199], v[216:217], off offset:528
	v_mul_f32_e32 v114, v121, v121
	v_fmac_f32_e32 v112, v116, v116
	v_fmac_f32_e32 v113, v118, v118
	v_mul_f32_e32 v115, v123, v123
	v_fmac_f32_e32 v114, v120, v120
	v_add_f32_e32 v112, v112, v113
	v_add_f32_e32 v112, v112, v114
	v_fmac_f32_e32 v115, v122, v122
	v_add_f32_e32 v112, v115, v112
	v_add_f32_e32 v112, v124, v112
	ds_bpermute_b32 v113, v176, v112
	global_store_dwordx4 v[168:169], v[116:119], off offset:512
	global_store_dwordx4 v[168:169], v[120:123], off offset:528
	v_cvt_pk_bf16_f32 v114, v116, v117
	v_cvt_pk_bf16_f32 v115, v118, v119
	s_waitcnt lgkmcnt(0)
	v_add_f32_e32 v112, v112, v113
	ds_bpermute_b32 v113, v177, v112
	v_cvt_pk_bf16_f32 v116, v120, v121
	v_cvt_pk_bf16_f32 v117, v122, v123
	global_store_dwordx4 v[172:173], v[114:117], off offset:256
	s_and_saveexec_b64 s[60:61], s[6:7]
	s_cbranch_execz .LBB0_815
	v_lshl_add_u64 v[114:115], v[148:149], 2, s[46:47]
	s_waitcnt lgkmcnt(0)
	v_add_f32_e32 v112, v112, v113
	global_atomic_add_f32 v[114:115], v112, off
.LBB0_815:
	s_or_b64 exec, exec, s[60:61]
	v_or_b32_e32 v112, 16, v148
	s_waitcnt lgkmcnt(0)
	v_ashrrev_i32_e32 v113, 31, v112
	v_lshlrev_b64 v[122:123], 13, v[112:113]
	v_lshl_add_u64 v[114:115], s[0:1], 0, v[122:123]
	v_lshl_add_u64 v[124:125], v[114:115], 0, v[146:147]
	v_lshlrev_b64 v[126:127], 12, v[112:113]
	v_lshl_add_u64 v[122:123], s[10:11], 0, v[122:123]
	v_lshl_add_u64 v[126:127], s[16:17], 0, v[126:127]
	v_lshl_add_u64 v[122:123], v[122:123], 0, v[146:147]
	v_lshl_add_u64 v[126:127], v[144:145], 1, v[126:127]
	s_waitcnt vmcnt(10)
	v_pk_add_f32 v[110:111], v[110:111], v[202:203]
	v_pk_add_f32 v[108:109], v[108:109], v[200:201]
	v_pk_add_f32 v[106:107], v[106:107], v[206:207]
	v_pk_add_f32 v[104:105], v[104:105], v[204:205]
	global_store_dwordx4 v[122:123], v[108:111], off
	global_store_dwordx4 v[122:123], v[104:107], off offset:16
	v_cvt_pk_bf16_f32 v114, v108, v109
	v_cvt_pk_bf16_f32 v115, v110, v111
	v_cvt_pk_bf16_f32 v116, v104, v105
	v_cvt_pk_bf16_f32 v117, v106, v107
	global_store_dwordx4 v[126:127], v[114:117], off
	s_nop 0
	v_mul_f32_e32 v109, v109, v109
	v_mul_f32_e32 v111, v111, v111
	v_mul_f32_e32 v105, v105, v105
	v_fmac_f32_e32 v109, v108, v108
	v_fmac_f32_e32 v111, v110, v110
	v_mul_f32_e32 v107, v107, v107
	v_fmac_f32_e32 v105, v104, v104
	v_add_f32_e32 v104, v109, v111
	v_fmac_f32_e32 v107, v106, v106
	v_add_f32_e32 v104, v104, v105
	v_add_f32_e32 v108, v107, v104
	v_pk_add_f32 v[102:103], v[102:103], v[210:211]
	v_pk_add_f32 v[100:101], v[100:101], v[208:209]
	v_pk_add_f32 v[104:105], v[96:97], v[212:213]
	v_mul_f32_e32 v96, v101, v101
	v_mul_f32_e32 v97, v103, v103
	v_pk_add_f32 v[106:107], v[98:99], v[214:215]
	v_lshl_add_u64 v[216:217], v[216:217], 0, s[98:99]
	global_load_dwordx4 v[200:203], v[216:217], off
	global_load_dwordx4 v[204:207], v[216:217], off offset:16
	global_load_dwordx4 v[208:211], v[216:217], off offset:512
	global_load_dwordx4 v[212:215], v[216:217], off offset:528
	v_mul_f32_e32 v98, v105, v105
	v_fmac_f32_e32 v96, v100, v100
	v_fmac_f32_e32 v97, v102, v102
	v_mul_f32_e32 v99, v107, v107
	v_fmac_f32_e32 v98, v104, v104
	v_add_f32_e32 v96, v96, v97
	v_add_f32_e32 v96, v96, v98
	v_fmac_f32_e32 v99, v106, v106
	v_add_f32_e32 v96, v99, v96
	v_add_f32_e32 v96, v108, v96
	ds_bpermute_b32 v97, v176, v96
	global_store_dwordx4 v[122:123], v[100:103], off offset:512
	global_store_dwordx4 v[122:123], v[104:107], off offset:528
	v_cvt_pk_bf16_f32 v98, v100, v101
	v_cvt_pk_bf16_f32 v99, v102, v103
	s_waitcnt lgkmcnt(0)
	v_add_f32_e32 v96, v96, v97
	ds_bpermute_b32 v97, v177, v96
	v_cvt_pk_bf16_f32 v100, v104, v105
	v_cvt_pk_bf16_f32 v101, v106, v107
	global_store_dwordx4 v[126:127], v[98:101], off offset:256
	s_and_saveexec_b64 s[60:61], s[6:7]
	s_cbranch_execz .LBB0_817
	v_lshl_add_u64 v[98:99], v[112:113], 2, s[46:47]
	s_waitcnt lgkmcnt(0)
	v_add_f32_e32 v96, v96, v97
	global_atomic_add_f32 v[98:99], v96, off
.LBB0_817:
	s_or_b64 exec, exec, s[60:61]
	v_or_b32_e32 v96, 32, v148
	s_waitcnt lgkmcnt(0)
	v_ashrrev_i32_e32 v97, 31, v96
	v_lshlrev_b64 v[106:107], 13, v[96:97]
	v_lshl_add_u64 v[98:99], s[0:1], 0, v[106:107]
	v_lshl_add_u64 v[108:109], v[98:99], 0, v[146:147]
	v_lshlrev_b64 v[110:111], 12, v[96:97]
	v_lshl_add_u64 v[106:107], s[10:11], 0, v[106:107]
	v_lshl_add_u64 v[110:111], s[16:17], 0, v[110:111]
	v_lshl_add_u64 v[106:107], v[106:107], 0, v[146:147]
	v_lshl_add_u64 v[110:111], v[144:145], 1, v[110:111]
	s_waitcnt vmcnt(14)
	v_pk_add_f32 v[94:95], v[94:95], v[186:187]
	v_pk_add_f32 v[92:93], v[92:93], v[184:185]
	v_pk_add_f32 v[90:91], v[90:91], v[190:191]
	v_pk_add_f32 v[88:89], v[88:89], v[188:189]
	global_store_dwordx4 v[106:107], v[92:95], off
	global_store_dwordx4 v[106:107], v[88:91], off offset:16
	v_cvt_pk_bf16_f32 v98, v92, v93
	v_cvt_pk_bf16_f32 v99, v94, v95
	v_cvt_pk_bf16_f32 v100, v88, v89
	v_cvt_pk_bf16_f32 v101, v90, v91
	global_store_dwordx4 v[110:111], v[98:101], off
	s_nop 0
	v_mul_f32_e32 v93, v93, v93
	v_mul_f32_e32 v95, v95, v95
	v_mul_f32_e32 v89, v89, v89
	v_fmac_f32_e32 v93, v92, v92
	v_fmac_f32_e32 v95, v94, v94
	v_mul_f32_e32 v91, v91, v91
	v_fmac_f32_e32 v89, v88, v88
	v_add_f32_e32 v88, v93, v95
	v_fmac_f32_e32 v91, v90, v90
	v_add_f32_e32 v88, v88, v89
	v_add_f32_e32 v92, v91, v88
	v_pk_add_f32 v[86:87], v[86:87], v[194:195]
	v_pk_add_f32 v[84:85], v[84:85], v[192:193]
	v_pk_add_f32 v[88:89], v[80:81], v[196:197]
	v_mul_f32_e32 v80, v85, v85
	v_mul_f32_e32 v81, v87, v87
	v_pk_add_f32 v[90:91], v[82:83], v[198:199]
	v_lshl_add_u64 v[216:217], v[216:217], 0, s[100:101]
	global_load_dwordx4 v[184:187], v[216:217], off
	global_load_dwordx4 v[188:191], v[216:217], off offset:16
	global_load_dwordx4 v[192:195], v[216:217], off offset:512
	global_load_dwordx4 v[196:199], v[216:217], off offset:528
	v_mul_f32_e32 v82, v89, v89
	v_fmac_f32_e32 v80, v84, v84
	v_fmac_f32_e32 v81, v86, v86
	v_mul_f32_e32 v83, v91, v91
	v_fmac_f32_e32 v82, v88, v88
	v_add_f32_e32 v80, v80, v81
	v_add_f32_e32 v80, v80, v82
	v_fmac_f32_e32 v83, v90, v90
	v_add_f32_e32 v80, v83, v80
	v_add_f32_e32 v80, v92, v80
	ds_bpermute_b32 v81, v176, v80
	global_store_dwordx4 v[106:107], v[84:87], off offset:512
	global_store_dwordx4 v[106:107], v[88:91], off offset:528
	v_cvt_pk_bf16_f32 v82, v84, v85
	v_cvt_pk_bf16_f32 v83, v86, v87
	s_waitcnt lgkmcnt(0)
	v_add_f32_e32 v80, v80, v81
	ds_bpermute_b32 v81, v177, v80
	v_cvt_pk_bf16_f32 v84, v88, v89
	v_cvt_pk_bf16_f32 v85, v90, v91
	global_store_dwordx4 v[110:111], v[82:85], off offset:256
	s_and_saveexec_b64 s[60:61], s[6:7]
	s_cbranch_execz .LBB0_819
	v_lshl_add_u64 v[82:83], v[96:97], 2, s[46:47]
	s_waitcnt lgkmcnt(0)
	v_add_f32_e32 v80, v80, v81
	global_atomic_add_f32 v[82:83], v80, off
.LBB0_819:
	s_or_b64 exec, exec, s[60:61]
	v_or_b32_e32 v80, 48, v148
	s_waitcnt lgkmcnt(0)
	v_ashrrev_i32_e32 v81, 31, v80
	v_lshlrev_b64 v[90:91], 13, v[80:81]
	v_lshl_add_u64 v[82:83], s[0:1], 0, v[90:91]
	v_lshl_add_u64 v[92:93], v[82:83], 0, v[146:147]
	v_lshlrev_b64 v[94:95], 12, v[80:81]
	v_lshl_add_u64 v[90:91], s[10:11], 0, v[90:91]
	v_lshl_add_u64 v[94:95], s[16:17], 0, v[94:95]
	v_lshl_add_u64 v[90:91], v[90:91], 0, v[146:147]
	v_lshl_add_u64 v[94:95], v[144:145], 1, v[94:95]
	s_waitcnt vmcnt(14)
	v_pk_add_f32 v[78:79], v[78:79], v[202:203]
	v_pk_add_f32 v[76:77], v[76:77], v[200:201]
	v_pk_add_f32 v[74:75], v[74:75], v[206:207]
	v_pk_add_f32 v[72:73], v[72:73], v[204:205]
	global_store_dwordx4 v[90:91], v[76:79], off
	global_store_dwordx4 v[90:91], v[72:75], off offset:16
	v_cvt_pk_bf16_f32 v82, v76, v77
	v_cvt_pk_bf16_f32 v83, v78, v79
	v_cvt_pk_bf16_f32 v84, v72, v73
	v_cvt_pk_bf16_f32 v85, v74, v75
	global_store_dwordx4 v[94:95], v[82:85], off
	s_nop 0
	v_mul_f32_e32 v77, v77, v77
	v_mul_f32_e32 v79, v79, v79
	v_mul_f32_e32 v73, v73, v73
	v_fmac_f32_e32 v77, v76, v76
	v_fmac_f32_e32 v79, v78, v78
	v_mul_f32_e32 v75, v75, v75
	v_fmac_f32_e32 v73, v72, v72
	v_add_f32_e32 v72, v77, v79
	v_fmac_f32_e32 v75, v74, v74
	v_add_f32_e32 v72, v72, v73
	v_add_f32_e32 v76, v75, v72
	v_pk_add_f32 v[70:71], v[70:71], v[210:211]
	v_pk_add_f32 v[68:69], v[68:69], v[208:209]
	v_pk_add_f32 v[72:73], v[64:65], v[212:213]
	v_mul_f32_e32 v64, v69, v69
	v_mul_f32_e32 v65, v71, v71
	v_pk_add_f32 v[74:75], v[66:67], v[214:215]
	v_lshl_add_u64 v[216:217], v[216:217], 0, s[98:99]
	global_load_dwordx4 v[200:203], v[216:217], off
	global_load_dwordx4 v[204:207], v[216:217], off offset:16
	global_load_dwordx4 v[208:211], v[216:217], off offset:512
	global_load_dwordx4 v[212:215], v[216:217], off offset:528
	v_mul_f32_e32 v66, v73, v73
	v_fmac_f32_e32 v64, v68, v68
	v_fmac_f32_e32 v65, v70, v70
	v_mul_f32_e32 v67, v75, v75
	v_fmac_f32_e32 v66, v72, v72
	v_add_f32_e32 v64, v64, v65
	v_add_f32_e32 v64, v64, v66
	v_fmac_f32_e32 v67, v74, v74
	v_add_f32_e32 v64, v67, v64
	v_add_f32_e32 v64, v76, v64
	ds_bpermute_b32 v65, v176, v64
	global_store_dwordx4 v[90:91], v[68:71], off offset:512
	global_store_dwordx4 v[90:91], v[72:75], off offset:528
	v_cvt_pk_bf16_f32 v66, v68, v69
	v_cvt_pk_bf16_f32 v67, v70, v71
	s_waitcnt lgkmcnt(0)
	v_add_f32_e32 v64, v64, v65
	ds_bpermute_b32 v65, v177, v64
	v_cvt_pk_bf16_f32 v68, v72, v73
	v_cvt_pk_bf16_f32 v69, v74, v75
	global_store_dwordx4 v[94:95], v[66:69], off offset:256
	s_and_saveexec_b64 s[60:61], s[6:7]
	s_cbranch_execz .LBB0_821
	v_lshl_add_u64 v[66:67], v[80:81], 2, s[46:47]
	s_waitcnt lgkmcnt(0)
	v_add_f32_e32 v64, v64, v65
	global_atomic_add_f32 v[66:67], v64, off
.LBB0_821:
	s_or_b64 exec, exec, s[60:61]
	v_or_b32_e32 v64, 0x80, v148
	s_waitcnt lgkmcnt(0)
	v_ashrrev_i32_e32 v65, 31, v64
	v_lshlrev_b64 v[74:75], 13, v[64:65]
	v_lshl_add_u64 v[66:67], s[0:1], 0, v[74:75]
	v_lshl_add_u64 v[76:77], v[66:67], 0, v[146:147]
	v_lshlrev_b64 v[78:79], 12, v[64:65]
	v_lshl_add_u64 v[74:75], s[10:11], 0, v[74:75]
	v_lshl_add_u64 v[78:79], s[16:17], 0, v[78:79]
	v_lshl_add_u64 v[74:75], v[74:75], 0, v[146:147]
	v_lshl_add_u64 v[78:79], v[144:145], 1, v[78:79]
	s_waitcnt vmcnt(14)
	v_pk_add_f32 v[62:63], v[62:63], v[186:187]
	v_pk_add_f32 v[60:61], v[60:61], v[184:185]
	v_pk_add_f32 v[58:59], v[58:59], v[190:191]
	v_pk_add_f32 v[56:57], v[56:57], v[188:189]
	global_store_dwordx4 v[74:75], v[60:63], off
	global_store_dwordx4 v[74:75], v[56:59], off offset:16
	v_cvt_pk_bf16_f32 v66, v60, v61
	v_cvt_pk_bf16_f32 v67, v62, v63
	v_cvt_pk_bf16_f32 v68, v56, v57
	v_cvt_pk_bf16_f32 v69, v58, v59
	global_store_dwordx4 v[78:79], v[66:69], off
	s_nop 0
	v_mul_f32_e32 v61, v61, v61
	v_mul_f32_e32 v63, v63, v63
	v_mul_f32_e32 v57, v57, v57
	v_fmac_f32_e32 v61, v60, v60
	v_fmac_f32_e32 v63, v62, v62
	v_mul_f32_e32 v59, v59, v59
	v_fmac_f32_e32 v57, v56, v56
	v_add_f32_e32 v56, v61, v63
	v_fmac_f32_e32 v59, v58, v58
	v_add_f32_e32 v56, v56, v57
	v_add_f32_e32 v60, v59, v56
	v_pk_add_f32 v[54:55], v[54:55], v[194:195]
	v_pk_add_f32 v[52:53], v[52:53], v[192:193]
	v_pk_add_f32 v[56:57], v[48:49], v[196:197]
	v_mul_f32_e32 v48, v53, v53
	v_mul_f32_e32 v49, v55, v55
	v_pk_add_f32 v[58:59], v[50:51], v[198:199]
	v_lshl_add_u64 v[216:217], v[216:217], 0, s[98:99]
	global_load_dwordx4 v[184:187], v[216:217], off
	global_load_dwordx4 v[188:191], v[216:217], off offset:16
	global_load_dwordx4 v[192:195], v[216:217], off offset:512
	global_load_dwordx4 v[196:199], v[216:217], off offset:528
	v_mul_f32_e32 v50, v57, v57
	v_fmac_f32_e32 v48, v52, v52
	v_fmac_f32_e32 v49, v54, v54
	v_mul_f32_e32 v51, v59, v59
	v_fmac_f32_e32 v50, v56, v56
	v_add_f32_e32 v48, v48, v49
	v_add_f32_e32 v48, v48, v50
	v_fmac_f32_e32 v51, v58, v58
	v_add_f32_e32 v48, v51, v48
	v_add_f32_e32 v48, v60, v48
	ds_bpermute_b32 v49, v176, v48
	global_store_dwordx4 v[74:75], v[52:55], off offset:512
	global_store_dwordx4 v[74:75], v[56:59], off offset:528
	v_cvt_pk_bf16_f32 v50, v52, v53
	v_cvt_pk_bf16_f32 v51, v54, v55
	s_waitcnt lgkmcnt(0)
	v_add_f32_e32 v48, v48, v49
	ds_bpermute_b32 v49, v177, v48
	v_cvt_pk_bf16_f32 v52, v56, v57
	v_cvt_pk_bf16_f32 v53, v58, v59
	global_store_dwordx4 v[78:79], v[50:53], off offset:256
	s_and_saveexec_b64 s[60:61], s[6:7]
	s_cbranch_execz .LBB0_823
	v_lshl_add_u64 v[50:51], v[64:65], 2, s[46:47]
	s_waitcnt lgkmcnt(0)
	v_add_f32_e32 v48, v48, v49
	global_atomic_add_f32 v[50:51], v48, off
.LBB0_823:
	s_or_b64 exec, exec, s[60:61]
	v_or_b32_e32 v48, 0x90, v148
	s_waitcnt lgkmcnt(0)
	v_ashrrev_i32_e32 v49, 31, v48
	v_lshlrev_b64 v[58:59], 13, v[48:49]
	v_lshl_add_u64 v[50:51], s[0:1], 0, v[58:59]
	v_lshl_add_u64 v[60:61], v[50:51], 0, v[146:147]
	v_lshlrev_b64 v[62:63], 12, v[48:49]
	v_lshl_add_u64 v[58:59], s[10:11], 0, v[58:59]
	v_lshl_add_u64 v[62:63], s[16:17], 0, v[62:63]
	v_lshl_add_u64 v[58:59], v[58:59], 0, v[146:147]
	v_lshl_add_u64 v[62:63], v[144:145], 1, v[62:63]
	s_waitcnt vmcnt(14)
	v_pk_add_f32 v[46:47], v[46:47], v[202:203]
	v_pk_add_f32 v[44:45], v[44:45], v[200:201]
	v_pk_add_f32 v[42:43], v[42:43], v[206:207]
	v_pk_add_f32 v[40:41], v[40:41], v[204:205]
	global_store_dwordx4 v[58:59], v[44:47], off
	global_store_dwordx4 v[58:59], v[40:43], off offset:16
	v_cvt_pk_bf16_f32 v50, v44, v45
	v_cvt_pk_bf16_f32 v51, v46, v47
	v_cvt_pk_bf16_f32 v52, v40, v41
	v_cvt_pk_bf16_f32 v53, v42, v43
	global_store_dwordx4 v[62:63], v[50:53], off
	s_nop 0
	v_mul_f32_e32 v45, v45, v45
	v_mul_f32_e32 v47, v47, v47
	v_mul_f32_e32 v41, v41, v41
	v_fmac_f32_e32 v45, v44, v44
	v_fmac_f32_e32 v47, v46, v46
	v_mul_f32_e32 v43, v43, v43
	v_fmac_f32_e32 v41, v40, v40
	v_add_f32_e32 v40, v45, v47
	v_fmac_f32_e32 v43, v42, v42
	v_add_f32_e32 v40, v40, v41
	v_add_f32_e32 v44, v43, v40
	v_pk_add_f32 v[38:39], v[38:39], v[210:211]
	v_pk_add_f32 v[36:37], v[36:37], v[208:209]
	v_pk_add_f32 v[40:41], v[32:33], v[212:213]
	v_mul_f32_e32 v32, v37, v37
	v_mul_f32_e32 v33, v39, v39
	v_pk_add_f32 v[42:43], v[34:35], v[214:215]
	v_lshl_add_u64 v[216:217], v[216:217], 0, s[98:99]
	global_load_dwordx4 v[200:203], v[216:217], off
	global_load_dwordx4 v[204:207], v[216:217], off offset:16
	global_load_dwordx4 v[208:211], v[216:217], off offset:512
	global_load_dwordx4 v[212:215], v[216:217], off offset:528
	v_mul_f32_e32 v34, v41, v41
	v_fmac_f32_e32 v32, v36, v36
	v_fmac_f32_e32 v33, v38, v38
	v_mul_f32_e32 v35, v43, v43
	v_fmac_f32_e32 v34, v40, v40
	v_add_f32_e32 v32, v32, v33
	v_add_f32_e32 v32, v32, v34
	v_fmac_f32_e32 v35, v42, v42
	v_add_f32_e32 v32, v35, v32
	v_add_f32_e32 v32, v44, v32
	ds_bpermute_b32 v33, v176, v32
	global_store_dwordx4 v[58:59], v[36:39], off offset:512
	global_store_dwordx4 v[58:59], v[40:43], off offset:528
	v_cvt_pk_bf16_f32 v34, v36, v37
	v_cvt_pk_bf16_f32 v35, v38, v39
	s_waitcnt lgkmcnt(0)
	v_add_f32_e32 v32, v32, v33
	ds_bpermute_b32 v33, v177, v32
	v_cvt_pk_bf16_f32 v36, v40, v41
	v_cvt_pk_bf16_f32 v37, v42, v43
	global_store_dwordx4 v[62:63], v[34:37], off offset:256
	s_and_saveexec_b64 s[60:61], s[6:7]
	s_cbranch_execz .LBB0_825
	v_lshl_add_u64 v[34:35], v[48:49], 2, s[46:47]
	s_waitcnt lgkmcnt(0)
	v_add_f32_e32 v32, v32, v33
	global_atomic_add_f32 v[34:35], v32, off
.LBB0_825:
	s_or_b64 exec, exec, s[60:61]
	v_or_b32_e32 v32, 0xa0, v148
	s_waitcnt lgkmcnt(0)
	v_ashrrev_i32_e32 v33, 31, v32
	v_lshlrev_b64 v[42:43], 13, v[32:33]
	v_lshl_add_u64 v[34:35], s[0:1], 0, v[42:43]
	v_lshl_add_u64 v[44:45], v[34:35], 0, v[146:147]
	v_lshlrev_b64 v[46:47], 12, v[32:33]
	v_lshl_add_u64 v[42:43], s[10:11], 0, v[42:43]
	v_lshl_add_u64 v[46:47], s[16:17], 0, v[46:47]
	v_lshl_add_u64 v[42:43], v[42:43], 0, v[146:147]
	v_lshl_add_u64 v[46:47], v[144:145], 1, v[46:47]
	s_waitcnt vmcnt(14)
	v_pk_add_f32 v[30:31], v[30:31], v[186:187]
	v_pk_add_f32 v[28:29], v[28:29], v[184:185]
	v_pk_add_f32 v[26:27], v[26:27], v[190:191]
	v_pk_add_f32 v[24:25], v[24:25], v[188:189]
	global_store_dwordx4 v[42:43], v[28:31], off
	global_store_dwordx4 v[42:43], v[24:27], off offset:16
	v_cvt_pk_bf16_f32 v34, v28, v29
	v_cvt_pk_bf16_f32 v35, v30, v31
	v_cvt_pk_bf16_f32 v36, v24, v25
	v_cvt_pk_bf16_f32 v37, v26, v27
	global_store_dwordx4 v[46:47], v[34:37], off
	s_nop 0
	v_mul_f32_e32 v29, v29, v29
	v_mul_f32_e32 v31, v31, v31
	v_mul_f32_e32 v25, v25, v25
	v_fmac_f32_e32 v29, v28, v28
	v_fmac_f32_e32 v31, v30, v30
	v_mul_f32_e32 v27, v27, v27
	v_fmac_f32_e32 v25, v24, v24
	v_add_f32_e32 v24, v29, v31
	v_fmac_f32_e32 v27, v26, v26
	v_add_f32_e32 v24, v24, v25
	v_add_f32_e32 v28, v27, v24
	v_pk_add_f32 v[22:23], v[22:23], v[194:195]
	v_pk_add_f32 v[20:21], v[20:21], v[192:193]
	v_pk_add_f32 v[24:25], v[16:17], v[196:197]
	v_mul_f32_e32 v16, v21, v21
	v_mul_f32_e32 v17, v23, v23
	v_pk_add_f32 v[26:27], v[18:19], v[198:199]
	v_mul_f32_e32 v18, v25, v25
	v_fmac_f32_e32 v16, v20, v20
	v_fmac_f32_e32 v17, v22, v22
	v_mul_f32_e32 v19, v27, v27
	v_fmac_f32_e32 v18, v24, v24
	v_add_f32_e32 v16, v16, v17
	v_add_f32_e32 v16, v16, v18
	v_fmac_f32_e32 v19, v26, v26
	v_add_f32_e32 v16, v19, v16
	v_add_f32_e32 v16, v28, v16
	ds_bpermute_b32 v17, v176, v16
	global_store_dwordx4 v[42:43], v[20:23], off offset:512
	global_store_dwordx4 v[42:43], v[24:27], off offset:528
	v_cvt_pk_bf16_f32 v18, v20, v21
	v_cvt_pk_bf16_f32 v19, v22, v23
	s_waitcnt lgkmcnt(0)
	v_add_f32_e32 v16, v16, v17
	ds_bpermute_b32 v17, v177, v16
	v_cvt_pk_bf16_f32 v20, v24, v25
	v_cvt_pk_bf16_f32 v21, v26, v27
	global_store_dwordx4 v[46:47], v[18:21], off offset:256
	s_and_saveexec_b64 s[60:61], s[6:7]
	s_cbranch_execz .LBB0_827
	v_lshl_add_u64 v[18:19], v[32:33], 2, s[46:47]
	s_waitcnt lgkmcnt(0)
	v_add_f32_e32 v16, v16, v17
	global_atomic_add_f32 v[18:19], v16, off
.LBB0_827:
	s_or_b64 exec, exec, s[60:61]
	v_or_b32_e32 v16, 0xb0, v148
	s_waitcnt lgkmcnt(0)
	v_ashrrev_i32_e32 v17, 31, v16
	v_lshlrev_b64 v[26:27], 13, v[16:17]
	v_lshl_add_u64 v[18:19], s[0:1], 0, v[26:27]
	v_lshl_add_u64 v[28:29], v[18:19], 0, v[146:147]
	v_lshlrev_b64 v[30:31], 12, v[16:17]
	v_lshl_add_u64 v[26:27], s[10:11], 0, v[26:27]
	v_lshl_add_u64 v[30:31], s[16:17], 0, v[30:31]
	v_lshl_add_u64 v[26:27], v[26:27], 0, v[146:147]
	v_lshl_add_u64 v[30:31], v[144:145], 1, v[30:31]
	s_waitcnt vmcnt(10)
	v_pk_add_f32 v[14:15], v[14:15], v[202:203]
	v_pk_add_f32 v[12:13], v[12:13], v[200:201]
	v_pk_add_f32 v[10:11], v[10:11], v[206:207]
	v_pk_add_f32 v[8:9], v[8:9], v[204:205]
	global_store_dwordx4 v[26:27], v[12:15], off
	global_store_dwordx4 v[26:27], v[8:11], off offset:16
	v_cvt_pk_bf16_f32 v18, v12, v13
	v_cvt_pk_bf16_f32 v19, v14, v15
	v_cvt_pk_bf16_f32 v20, v8, v9
	v_cvt_pk_bf16_f32 v21, v10, v11
	global_store_dwordx4 v[30:31], v[18:21], off
	s_nop 0
	v_mul_f32_e32 v13, v13, v13
	v_mul_f32_e32 v15, v15, v15
	v_mul_f32_e32 v9, v9, v9
	v_fmac_f32_e32 v13, v12, v12
	v_fmac_f32_e32 v15, v14, v14
	v_mul_f32_e32 v11, v11, v11
	v_fmac_f32_e32 v9, v8, v8
	v_add_f32_e32 v8, v13, v15
	v_fmac_f32_e32 v11, v10, v10
	v_add_f32_e32 v8, v8, v9
	v_add_f32_e32 v12, v11, v8
	v_pk_add_f32 v[6:7], v[6:7], v[210:211]
	v_pk_add_f32 v[4:5], v[4:5], v[208:209]
	v_pk_add_f32 v[8:9], v[0:1], v[212:213]
	v_mul_f32_e32 v0, v5, v5
	v_mul_f32_e32 v1, v7, v7
	v_pk_add_f32 v[10:11], v[2:3], v[214:215]
	v_mul_f32_e32 v2, v9, v9
	v_fmac_f32_e32 v0, v4, v4
	v_fmac_f32_e32 v1, v6, v6
	v_mul_f32_e32 v3, v11, v11
	v_fmac_f32_e32 v2, v8, v8
	v_add_f32_e32 v0, v0, v1
	v_add_f32_e32 v0, v0, v2
	v_fmac_f32_e32 v3, v10, v10
	v_add_f32_e32 v0, v3, v0
	v_add_f32_e32 v0, v12, v0
	ds_bpermute_b32 v1, v176, v0
	global_store_dwordx4 v[26:27], v[4:7], off offset:512
	global_store_dwordx4 v[26:27], v[8:11], off offset:528
	v_cvt_pk_bf16_f32 v2, v4, v5
	v_cvt_pk_bf16_f32 v3, v6, v7
	s_waitcnt lgkmcnt(0)
	v_add_f32_e32 v0, v0, v1
	ds_bpermute_b32 v1, v177, v0
	v_cvt_pk_bf16_f32 v4, v8, v9
	v_cvt_pk_bf16_f32 v5, v10, v11
	global_store_dwordx4 v[30:31], v[2:5], off offset:256
	s_and_saveexec_b64 s[60:61], s[6:7]
	s_cbranch_execz .LBB0_829
	v_lshl_add_u64 v[2:3], v[16:17], 2, s[46:47]
	s_waitcnt lgkmcnt(0)
	v_add_f32_e32 v0, v0, v1
	global_atomic_add_f32 v[2:3], v0, off

.LBB0_1432:
	v_lshl_or_b32 v148, s50, 8, v151
	v_lshl_or_b32 v144, s52, 8, v152
	v_ashrrev_i32_e32 v149, 31, v148
	v_lshlrev_b64 v[164:165], 13, v[148:149]
	v_ashrrev_i32_e32 v145, 31, v144
	v_lshl_add_u64 v[156:157], s[0:1], 0, v[164:165]
	v_lshlrev_b64 v[146:147], 2, v[144:145]
	v_lshl_add_u64 v[166:167], v[156:157], 0, v[146:147]
	s_mov_b32 s98, 0x20000
	s_mov_b32 s99, 0
	s_mov_b32 s100, 0xa0000
	s_mov_b32 s101, 0
	global_load_dwordx4 v[184:187], v[166:167], off
	global_load_dwordx4 v[188:191], v[166:167], off offset:16
	global_load_dwordx4 v[192:195], v[166:167], off offset:512
	global_load_dwordx4 v[196:199], v[166:167], off offset:528
	v_lshl_add_u64 v[216:217], v[166:167], 0, s[98:99]
	global_load_dwordx4 v[200:203], v[216:217], off
	global_load_dwordx4 v[204:207], v[216:217], off offset:16
	global_load_dwordx4 v[208:211], v[216:217], off offset:512
	global_load_dwordx4 v[212:215], v[216:217], off offset:528
	v_lshlrev_b64 v[168:169], 12, v[148:149]
	v_lshl_add_u64 v[164:165], s[10:11], 0, v[164:165]
	v_lshl_add_u64 v[168:169], s[16:17], 0, v[168:169]
	v_lshl_add_u64 v[164:165], v[164:165], 0, v[146:147]
	v_lshl_add_u64 v[168:169], v[144:145], 1, v[168:169]
	s_waitcnt vmcnt(3)
	v_pk_add_f32 v[126:127], v[126:127], v[186:187]
	v_pk_add_f32 v[124:125], v[124:125], v[184:185]
	v_pk_add_f32 v[122:123], v[122:123], v[190:191]
	v_pk_add_f32 v[120:121], v[120:121], v[188:189]
	global_store_dwordx4 v[164:165], v[124:127], off
	global_store_dwordx4 v[164:165], v[120:123], off offset:16
	v_cvt_pk_bf16_f32 v156, v124, v125
	v_cvt_pk_bf16_f32 v157, v126, v127
	v_cvt_pk_bf16_f32 v158, v120, v121
	v_cvt_pk_bf16_f32 v159, v122, v123
	global_store_dwordx4 v[168:169], v[156:159], off
	s_nop 0
	v_mul_f32_e32 v125, v125, v125
	v_mul_f32_e32 v127, v127, v127
	v_mul_f32_e32 v121, v121, v121
	v_fmac_f32_e32 v125, v124, v124
	v_fmac_f32_e32 v127, v126, v126
	v_mul_f32_e32 v123, v123, v123
	v_fmac_f32_e32 v121, v120, v120
	v_add_f32_e32 v120, v125, v127
	v_fmac_f32_e32 v123, v122, v122
	v_add_f32_e32 v120, v120, v121
	v_add_f32_e32 v124, v123, v120
	v_pk_add_f32 v[118:119], v[118:119], v[194:195]
	v_pk_add_f32 v[116:117], v[116:117], v[192:193]
	v_pk_add_f32 v[120:121], v[112:113], v[196:197]
	v_mul_f32_e32 v112, v117, v117
	v_mul_f32_e32 v113, v119, v119
	v_pk_add_f32 v[122:123], v[114:115], v[198:199]
	v_lshl_add_u64 v[216:217], v[216:217], 0, s[98:99]
	global_load_dwordx4 v[184:187], v[216:217], off
	global_load_dwordx4 v[188:191], v[216:217], off offset:16
	global_load_dwordx4 v[192:195], v[216:217], off offset:512
	global_load_dwordx4 v[196:199], v[216:217], off offset:528
	v_mul_f32_e32 v114, v121, v121
	v_fmac_f32_e32 v112, v116, v116
	v_fmac_f32_e32 v113, v118, v118
	v_mul_f32_e32 v115, v123, v123
	v_fmac_f32_e32 v114, v120, v120
	v_add_f32_e32 v112, v112, v113
	v_add_f32_e32 v112, v112, v114
	v_fmac_f32_e32 v115, v122, v122
	v_add_f32_e32 v112, v115, v112
	v_add_f32_e32 v112, v124, v112
	ds_bpermute_b32 v113, v176, v112
	global_store_dwordx4 v[164:165], v[116:119], off offset:512
	global_store_dwordx4 v[164:165], v[120:123], off offset:528
	v_cvt_pk_bf16_f32 v114, v116, v117
	v_cvt_pk_bf16_f32 v115, v118, v119
	s_waitcnt lgkmcnt(0)
	v_add_f32_e32 v112, v112, v113
	ds_bpermute_b32 v113, v177, v112
	v_cvt_pk_bf16_f32 v116, v120, v121
	v_cvt_pk_bf16_f32 v117, v122, v123
	global_store_dwordx4 v[168:169], v[114:117], off offset:256
	s_and_saveexec_b64 s[50:51], s[6:7]
	s_cbranch_execz .LBB0_1434
	v_lshl_add_u64 v[114:115], v[148:149], 2, s[38:39]
	s_waitcnt lgkmcnt(0)
	v_add_f32_e32 v112, v112, v113
	global_atomic_add_f32 v[114:115], v112, off
.LBB0_1434:
	s_or_b64 exec, exec, s[50:51]
	v_or_b32_e32 v112, 16, v148
	s_waitcnt lgkmcnt(0)
	v_ashrrev_i32_e32 v113, 31, v112
	v_lshlrev_b64 v[122:123], 13, v[112:113]
	v_lshl_add_u64 v[114:115], s[0:1], 0, v[122:123]
	v_lshl_add_u64 v[124:125], v[114:115], 0, v[146:147]
	v_lshlrev_b64 v[126:127], 12, v[112:113]
	v_lshl_add_u64 v[122:123], s[10:11], 0, v[122:123]
	v_lshl_add_u64 v[126:127], s[16:17], 0, v[126:127]
	v_lshl_add_u64 v[122:123], v[122:123], 0, v[146:147]
	v_lshl_add_u64 v[126:127], v[144:145], 1, v[126:127]
	s_waitcnt vmcnt(10)
	v_pk_add_f32 v[110:111], v[110:111], v[202:203]
	v_pk_add_f32 v[108:109], v[108:109], v[200:201]
	v_pk_add_f32 v[106:107], v[106:107], v[206:207]
	v_pk_add_f32 v[104:105], v[104:105], v[204:205]
	global_store_dwordx4 v[122:123], v[108:111], off
	global_store_dwordx4 v[122:123], v[104:107], off offset:16
	v_cvt_pk_bf16_f32 v114, v108, v109
	v_cvt_pk_bf16_f32 v115, v110, v111
	v_cvt_pk_bf16_f32 v116, v104, v105
	v_cvt_pk_bf16_f32 v117, v106, v107
	global_store_dwordx4 v[126:127], v[114:117], off
	s_nop 0
	v_mul_f32_e32 v109, v109, v109
	v_mul_f32_e32 v111, v111, v111
	v_mul_f32_e32 v105, v105, v105
	v_fmac_f32_e32 v109, v108, v108
	v_fmac_f32_e32 v111, v110, v110
	v_mul_f32_e32 v107, v107, v107
	v_fmac_f32_e32 v105, v104, v104
	v_add_f32_e32 v104, v109, v111
	v_fmac_f32_e32 v107, v106, v106
	v_add_f32_e32 v104, v104, v105
	v_add_f32_e32 v108, v107, v104
	v_pk_add_f32 v[102:103], v[102:103], v[210:211]
	v_pk_add_f32 v[100:101], v[100:101], v[208:209]
	v_pk_add_f32 v[104:105], v[96:97], v[212:213]
	v_mul_f32_e32 v96, v101, v101
	v_mul_f32_e32 v97, v103, v103
	v_pk_add_f32 v[106:107], v[98:99], v[214:215]
	v_lshl_add_u64 v[216:217], v[216:217], 0, s[98:99]
	global_load_dwordx4 v[200:203], v[216:217], off
	global_load_dwordx4 v[204:207], v[216:217], off offset:16
	global_load_dwordx4 v[208:211], v[216:217], off offset:512
	global_load_dwordx4 v[212:215], v[216:217], off offset:528
	v_mul_f32_e32 v98, v105, v105
	v_fmac_f32_e32 v96, v100, v100
	v_fmac_f32_e32 v97, v102, v102
	v_mul_f32_e32 v99, v107, v107
	v_fmac_f32_e32 v98, v104, v104
	v_add_f32_e32 v96, v96, v97
	v_add_f32_e32 v96, v96, v98
	v_fmac_f32_e32 v99, v106, v106
	v_add_f32_e32 v96, v99, v96
	v_add_f32_e32 v96, v108, v96
	ds_bpermute_b32 v97, v176, v96
	global_store_dwordx4 v[122:123], v[100:103], off offset:512
	global_store_dwordx4 v[122:123], v[104:107], off offset:528
	v_cvt_pk_bf16_f32 v98, v100, v101
	v_cvt_pk_bf16_f32 v99, v102, v103
	s_waitcnt lgkmcnt(0)
	v_add_f32_e32 v96, v96, v97
	ds_bpermute_b32 v97, v177, v96
	v_cvt_pk_bf16_f32 v100, v104, v105
	v_cvt_pk_bf16_f32 v101, v106, v107
	global_store_dwordx4 v[126:127], v[98:101], off offset:256
	s_and_saveexec_b64 s[50:51], s[6:7]
	s_cbranch_execz .LBB0_1436
	v_lshl_add_u64 v[98:99], v[112:113], 2, s[38:39]
	s_waitcnt lgkmcnt(0)
	v_add_f32_e32 v96, v96, v97
	global_atomic_add_f32 v[98:99], v96, off
.LBB0_1436:
	s_or_b64 exec, exec, s[50:51]
	v_or_b32_e32 v96, 32, v148
	s_waitcnt lgkmcnt(0)
	v_ashrrev_i32_e32 v97, 31, v96
	v_lshlrev_b64 v[106:107], 13, v[96:97]
	v_lshl_add_u64 v[98:99], s[0:1], 0, v[106:107]
	v_lshl_add_u64 v[108:109], v[98:99], 0, v[146:147]
	v_lshlrev_b64 v[110:111], 12, v[96:97]
	v_lshl_add_u64 v[106:107], s[10:11], 0, v[106:107]
	v_lshl_add_u64 v[110:111], s[16:17], 0, v[110:111]
	v_lshl_add_u64 v[106:107], v[106:107], 0, v[146:147]
	v_lshl_add_u64 v[110:111], v[144:145], 1, v[110:111]
	s_waitcnt vmcnt(14)
	v_pk_add_f32 v[94:95], v[94:95], v[186:187]
	v_pk_add_f32 v[92:93], v[92:93], v[184:185]
	v_pk_add_f32 v[90:91], v[90:91], v[190:191]
	v_pk_add_f32 v[88:89], v[88:89], v[188:189]
	global_store_dwordx4 v[106:107], v[92:95], off
	global_store_dwordx4 v[106:107], v[88:91], off offset:16
	v_cvt_pk_bf16_f32 v98, v92, v93
	v_cvt_pk_bf16_f32 v99, v94, v95
	v_cvt_pk_bf16_f32 v100, v88, v89
	v_cvt_pk_bf16_f32 v101, v90, v91
	global_store_dwordx4 v[110:111], v[98:101], off
	s_nop 0
	v_mul_f32_e32 v93, v93, v93
	v_mul_f32_e32 v95, v95, v95
	v_mul_f32_e32 v89, v89, v89
	v_fmac_f32_e32 v93, v92, v92
	v_fmac_f32_e32 v95, v94, v94
	v_mul_f32_e32 v91, v91, v91
	v_fmac_f32_e32 v89, v88, v88
	v_add_f32_e32 v88, v93, v95
	v_fmac_f32_e32 v91, v90, v90
	v_add_f32_e32 v88, v88, v89
	v_add_f32_e32 v92, v91, v88
	v_pk_add_f32 v[86:87], v[86:87], v[194:195]
	v_pk_add_f32 v[84:85], v[84:85], v[192:193]
	v_pk_add_f32 v[88:89], v[80:81], v[196:197]
	v_mul_f32_e32 v80, v85, v85
	v_mul_f32_e32 v81, v87, v87
	v_pk_add_f32 v[90:91], v[82:83], v[198:199]
	v_lshl_add_u64 v[216:217], v[216:217], 0, s[100:101]
	global_load_dwordx4 v[184:187], v[216:217], off
	global_load_dwordx4 v[188:191], v[216:217], off offset:16
	global_load_dwordx4 v[192:195], v[216:217], off offset:512
	global_load_dwordx4 v[196:199], v[216:217], off offset:528
	v_mul_f32_e32 v82, v89, v89
	v_fmac_f32_e32 v80, v84, v84
	v_fmac_f32_e32 v81, v86, v86
	v_mul_f32_e32 v83, v91, v91
	v_fmac_f32_e32 v82, v88, v88
	v_add_f32_e32 v80, v80, v81
	v_add_f32_e32 v80, v80, v82
	v_fmac_f32_e32 v83, v90, v90
	v_add_f32_e32 v80, v83, v80
	v_add_f32_e32 v80, v92, v80
	ds_bpermute_b32 v81, v176, v80
	global_store_dwordx4 v[106:107], v[84:87], off offset:512
	global_store_dwordx4 v[106:107], v[88:91], off offset:528
	v_cvt_pk_bf16_f32 v82, v84, v85
	v_cvt_pk_bf16_f32 v83, v86, v87
	s_waitcnt lgkmcnt(0)
	v_add_f32_e32 v80, v80, v81
	ds_bpermute_b32 v81, v177, v80
	v_cvt_pk_bf16_f32 v84, v88, v89
	v_cvt_pk_bf16_f32 v85, v90, v91
	global_store_dwordx4 v[110:111], v[82:85], off offset:256
	s_and_saveexec_b64 s[50:51], s[6:7]
	s_cbranch_execz .LBB0_1438
	v_lshl_add_u64 v[82:83], v[96:97], 2, s[38:39]
	s_waitcnt lgkmcnt(0)
	v_add_f32_e32 v80, v80, v81
	global_atomic_add_f32 v[82:83], v80, off
.LBB0_1438:
	s_or_b64 exec, exec, s[50:51]
	v_or_b32_e32 v80, 48, v148
	s_waitcnt lgkmcnt(0)
	v_ashrrev_i32_e32 v81, 31, v80
	v_lshlrev_b64 v[90:91], 13, v[80:81]
	v_lshl_add_u64 v[82:83], s[0:1], 0, v[90:91]
	v_lshl_add_u64 v[92:93], v[82:83], 0, v[146:147]
	v_lshlrev_b64 v[94:95], 12, v[80:81]
	v_lshl_add_u64 v[90:91], s[10:11], 0, v[90:91]
	v_lshl_add_u64 v[94:95], s[16:17], 0, v[94:95]
	v_lshl_add_u64 v[90:91], v[90:91], 0, v[146:147]
	v_lshl_add_u64 v[94:95], v[144:145], 1, v[94:95]
	s_waitcnt vmcnt(14)
	v_pk_add_f32 v[78:79], v[78:79], v[202:203]
	v_pk_add_f32 v[76:77], v[76:77], v[200:201]
	v_pk_add_f32 v[74:75], v[74:75], v[206:207]
	v_pk_add_f32 v[72:73], v[72:73], v[204:205]
	global_store_dwordx4 v[90:91], v[76:79], off
	global_store_dwordx4 v[90:91], v[72:75], off offset:16
	v_cvt_pk_bf16_f32 v82, v76, v77
	v_cvt_pk_bf16_f32 v83, v78, v79
	v_cvt_pk_bf16_f32 v84, v72, v73
	v_cvt_pk_bf16_f32 v85, v74, v75
	global_store_dwordx4 v[94:95], v[82:85], off
	s_nop 0
	v_mul_f32_e32 v77, v77, v77
	v_mul_f32_e32 v79, v79, v79
	v_mul_f32_e32 v73, v73, v73
	v_fmac_f32_e32 v77, v76, v76
	v_fmac_f32_e32 v79, v78, v78
	v_mul_f32_e32 v75, v75, v75
	v_fmac_f32_e32 v73, v72, v72
	v_add_f32_e32 v72, v77, v79
	v_fmac_f32_e32 v75, v74, v74
	v_add_f32_e32 v72, v72, v73
	v_add_f32_e32 v76, v75, v72
	v_pk_add_f32 v[70:71], v[70:71], v[210:211]
	v_pk_add_f32 v[68:69], v[68:69], v[208:209]
	v_pk_add_f32 v[72:73], v[64:65], v[212:213]
	v_mul_f32_e32 v64, v69, v69
	v_mul_f32_e32 v65, v71, v71
	v_pk_add_f32 v[74:75], v[66:67], v[214:215]
	v_lshl_add_u64 v[216:217], v[216:217], 0, s[98:99]
	global_load_dwordx4 v[200:203], v[216:217], off
	global_load_dwordx4 v[204:207], v[216:217], off offset:16
	global_load_dwordx4 v[208:211], v[216:217], off offset:512
	global_load_dwordx4 v[212:215], v[216:217], off offset:528
	v_mul_f32_e32 v66, v73, v73
	v_fmac_f32_e32 v64, v68, v68
	v_fmac_f32_e32 v65, v70, v70
	v_mul_f32_e32 v67, v75, v75
	v_fmac_f32_e32 v66, v72, v72
	v_add_f32_e32 v64, v64, v65
	v_add_f32_e32 v64, v64, v66
	v_fmac_f32_e32 v67, v74, v74
	v_add_f32_e32 v64, v67, v64
	v_add_f32_e32 v64, v76, v64
	ds_bpermute_b32 v65, v176, v64
	global_store_dwordx4 v[90:91], v[68:71], off offset:512
	global_store_dwordx4 v[90:91], v[72:75], off offset:528
	v_cvt_pk_bf16_f32 v66, v68, v69
	v_cvt_pk_bf16_f32 v67, v70, v71
	s_waitcnt lgkmcnt(0)
	v_add_f32_e32 v64, v64, v65
	ds_bpermute_b32 v65, v177, v64
	v_cvt_pk_bf16_f32 v68, v72, v73
	v_cvt_pk_bf16_f32 v69, v74, v75
	global_store_dwordx4 v[94:95], v[66:69], off offset:256
	s_and_saveexec_b64 s[50:51], s[6:7]
	s_cbranch_execz .LBB0_1440
	v_lshl_add_u64 v[66:67], v[80:81], 2, s[38:39]
	s_waitcnt lgkmcnt(0)
	v_add_f32_e32 v64, v64, v65
	global_atomic_add_f32 v[66:67], v64, off
.LBB0_1440:
	s_or_b64 exec, exec, s[50:51]
	v_or_b32_e32 v64, 0x80, v148
	s_waitcnt lgkmcnt(0)
	v_ashrrev_i32_e32 v65, 31, v64
	v_lshlrev_b64 v[74:75], 13, v[64:65]
	v_lshl_add_u64 v[66:67], s[0:1], 0, v[74:75]
	v_lshl_add_u64 v[76:77], v[66:67], 0, v[146:147]
	v_lshlrev_b64 v[78:79], 12, v[64:65]
	v_lshl_add_u64 v[74:75], s[10:11], 0, v[74:75]
	v_lshl_add_u64 v[78:79], s[16:17], 0, v[78:79]
	v_lshl_add_u64 v[74:75], v[74:75], 0, v[146:147]
	v_lshl_add_u64 v[78:79], v[144:145], 1, v[78:79]
	s_waitcnt vmcnt(14)
	v_pk_add_f32 v[62:63], v[62:63], v[186:187]
	v_pk_add_f32 v[60:61], v[60:61], v[184:185]
	v_pk_add_f32 v[58:59], v[58:59], v[190:191]
	v_pk_add_f32 v[56:57], v[56:57], v[188:189]
	global_store_dwordx4 v[74:75], v[60:63], off
	global_store_dwordx4 v[74:75], v[56:59], off offset:16
	v_cvt_pk_bf16_f32 v66, v60, v61
	v_cvt_pk_bf16_f32 v67, v62, v63
	v_cvt_pk_bf16_f32 v68, v56, v57
	v_cvt_pk_bf16_f32 v69, v58, v59
	global_store_dwordx4 v[78:79], v[66:69], off
	s_nop 0
	v_mul_f32_e32 v61, v61, v61
	v_mul_f32_e32 v63, v63, v63
	v_mul_f32_e32 v57, v57, v57
	v_fmac_f32_e32 v61, v60, v60
	v_fmac_f32_e32 v63, v62, v62
	v_mul_f32_e32 v59, v59, v59
	v_fmac_f32_e32 v57, v56, v56
	v_add_f32_e32 v56, v61, v63
	v_fmac_f32_e32 v59, v58, v58
	v_add_f32_e32 v56, v56, v57
	v_add_f32_e32 v60, v59, v56
	v_pk_add_f32 v[54:55], v[54:55], v[194:195]
	v_pk_add_f32 v[52:53], v[52:53], v[192:193]
	v_pk_add_f32 v[56:57], v[48:49], v[196:197]
	v_mul_f32_e32 v48, v53, v53
	v_mul_f32_e32 v49, v55, v55
	v_pk_add_f32 v[58:59], v[50:51], v[198:199]
	v_lshl_add_u64 v[216:217], v[216:217], 0, s[98:99]
	global_load_dwordx4 v[184:187], v[216:217], off
	global_load_dwordx4 v[188:191], v[216:217], off offset:16
	global_load_dwordx4 v[192:195], v[216:217], off offset:512
	global_load_dwordx4 v[196:199], v[216:217], off offset:528
	v_mul_f32_e32 v50, v57, v57
	v_fmac_f32_e32 v48, v52, v52
	v_fmac_f32_e32 v49, v54, v54
	v_mul_f32_e32 v51, v59, v59
	v_fmac_f32_e32 v50, v56, v56
	v_add_f32_e32 v48, v48, v49
	v_add_f32_e32 v48, v48, v50
	v_fmac_f32_e32 v51, v58, v58
	v_add_f32_e32 v48, v51, v48
	v_add_f32_e32 v48, v60, v48
	ds_bpermute_b32 v49, v176, v48
	global_store_dwordx4 v[74:75], v[52:55], off offset:512
	global_store_dwordx4 v[74:75], v[56:59], off offset:528
	v_cvt_pk_bf16_f32 v50, v52, v53
	v_cvt_pk_bf16_f32 v51, v54, v55
	s_waitcnt lgkmcnt(0)
	v_add_f32_e32 v48, v48, v49
	ds_bpermute_b32 v49, v177, v48
	v_cvt_pk_bf16_f32 v52, v56, v57
	v_cvt_pk_bf16_f32 v53, v58, v59
	global_store_dwordx4 v[78:79], v[50:53], off offset:256
	s_and_saveexec_b64 s[50:51], s[6:7]
	s_cbranch_execz .LBB0_1442
	v_lshl_add_u64 v[50:51], v[64:65], 2, s[38:39]
	s_waitcnt lgkmcnt(0)
	v_add_f32_e32 v48, v48, v49
	global_atomic_add_f32 v[50:51], v48, off
.LBB0_1442:
	s_or_b64 exec, exec, s[50:51]
	v_or_b32_e32 v48, 0x90, v148
	s_waitcnt lgkmcnt(0)
	v_ashrrev_i32_e32 v49, 31, v48
	v_lshlrev_b64 v[58:59], 13, v[48:49]
	v_lshl_add_u64 v[50:51], s[0:1], 0, v[58:59]
	v_lshl_add_u64 v[60:61], v[50:51], 0, v[146:147]
	v_lshlrev_b64 v[62:63], 12, v[48:49]
	v_lshl_add_u64 v[58:59], s[10:11], 0, v[58:59]
	v_lshl_add_u64 v[62:63], s[16:17], 0, v[62:63]
	v_lshl_add_u64 v[58:59], v[58:59], 0, v[146:147]
	v_lshl_add_u64 v[62:63], v[144:145], 1, v[62:63]
	s_waitcnt vmcnt(14)
	v_pk_add_f32 v[46:47], v[46:47], v[202:203]
	v_pk_add_f32 v[44:45], v[44:45], v[200:201]
	v_pk_add_f32 v[42:43], v[42:43], v[206:207]
	v_pk_add_f32 v[40:41], v[40:41], v[204:205]
	global_store_dwordx4 v[58:59], v[44:47], off
	global_store_dwordx4 v[58:59], v[40:43], off offset:16
	v_cvt_pk_bf16_f32 v50, v44, v45
	v_cvt_pk_bf16_f32 v51, v46, v47
	v_cvt_pk_bf16_f32 v52, v40, v41
	v_cvt_pk_bf16_f32 v53, v42, v43
	global_store_dwordx4 v[62:63], v[50:53], off
	s_nop 0
	v_mul_f32_e32 v45, v45, v45
	v_mul_f32_e32 v47, v47, v47
	v_mul_f32_e32 v41, v41, v41
	v_fmac_f32_e32 v45, v44, v44
	v_fmac_f32_e32 v47, v46, v46
	v_mul_f32_e32 v43, v43, v43
	v_fmac_f32_e32 v41, v40, v40
	v_add_f32_e32 v40, v45, v47
	v_fmac_f32_e32 v43, v42, v42
	v_add_f32_e32 v40, v40, v41
	v_add_f32_e32 v44, v43, v40
	v_pk_add_f32 v[38:39], v[38:39], v[210:211]
	v_pk_add_f32 v[36:37], v[36:37], v[208:209]
	v_pk_add_f32 v[40:41], v[32:33], v[212:213]
	v_mul_f32_e32 v32, v37, v37
	v_mul_f32_e32 v33, v39, v39
	v_pk_add_f32 v[42:43], v[34:35], v[214:215]
	v_lshl_add_u64 v[216:217], v[216:217], 0, s[98:99]
	global_load_dwordx4 v[200:203], v[216:217], off
	global_load_dwordx4 v[204:207], v[216:217], off offset:16
	global_load_dwordx4 v[208:211], v[216:217], off offset:512
	global_load_dwordx4 v[212:215], v[216:217], off offset:528
	v_mul_f32_e32 v34, v41, v41
	v_fmac_f32_e32 v32, v36, v36
	v_fmac_f32_e32 v33, v38, v38
	v_mul_f32_e32 v35, v43, v43
	v_fmac_f32_e32 v34, v40, v40
	v_add_f32_e32 v32, v32, v33
	v_add_f32_e32 v32, v32, v34
	v_fmac_f32_e32 v35, v42, v42
	v_add_f32_e32 v32, v35, v32
	v_add_f32_e32 v32, v44, v32
	ds_bpermute_b32 v33, v176, v32
	global_store_dwordx4 v[58:59], v[36:39], off offset:512
	global_store_dwordx4 v[58:59], v[40:43], off offset:528
	v_cvt_pk_bf16_f32 v34, v36, v37
	v_cvt_pk_bf16_f32 v35, v38, v39
	s_waitcnt lgkmcnt(0)
	v_add_f32_e32 v32, v32, v33
	ds_bpermute_b32 v33, v177, v32
	v_cvt_pk_bf16_f32 v36, v40, v41
	v_cvt_pk_bf16_f32 v37, v42, v43
	global_store_dwordx4 v[62:63], v[34:37], off offset:256
	s_and_saveexec_b64 s[50:51], s[6:7]
	s_cbranch_execz .LBB0_1444
	v_lshl_add_u64 v[34:35], v[48:49], 2, s[38:39]
	s_waitcnt lgkmcnt(0)
	v_add_f32_e32 v32, v32, v33
	global_atomic_add_f32 v[34:35], v32, off
.LBB0_1444:
	s_or_b64 exec, exec, s[50:51]
	v_or_b32_e32 v32, 0xa0, v148
	s_waitcnt lgkmcnt(0)
	v_ashrrev_i32_e32 v33, 31, v32
	v_lshlrev_b64 v[42:43], 13, v[32:33]
	v_lshl_add_u64 v[34:35], s[0:1], 0, v[42:43]
	v_lshl_add_u64 v[44:45], v[34:35], 0, v[146:147]
	v_lshlrev_b64 v[46:47], 12, v[32:33]
	v_lshl_add_u64 v[42:43], s[10:11], 0, v[42:43]
	v_lshl_add_u64 v[46:47], s[16:17], 0, v[46:47]
	v_lshl_add_u64 v[42:43], v[42:43], 0, v[146:147]
	v_lshl_add_u64 v[46:47], v[144:145], 1, v[46:47]
	s_waitcnt vmcnt(14)
	v_pk_add_f32 v[30:31], v[30:31], v[186:187]
	v_pk_add_f32 v[28:29], v[28:29], v[184:185]
	v_pk_add_f32 v[26:27], v[26:27], v[190:191]
	v_pk_add_f32 v[24:25], v[24:25], v[188:189]
	global_store_dwordx4 v[42:43], v[28:31], off
	global_store_dwordx4 v[42:43], v[24:27], off offset:16
	v_cvt_pk_bf16_f32 v34, v28, v29
	v_cvt_pk_bf16_f32 v35, v30, v31
	v_cvt_pk_bf16_f32 v36, v24, v25
	v_cvt_pk_bf16_f32 v37, v26, v27
	global_store_dwordx4 v[46:47], v[34:37], off
	s_nop 0
	v_mul_f32_e32 v29, v29, v29
	v_mul_f32_e32 v31, v31, v31
	v_mul_f32_e32 v25, v25, v25
	v_fmac_f32_e32 v29, v28, v28
	v_fmac_f32_e32 v31, v30, v30
	v_mul_f32_e32 v27, v27, v27
	v_fmac_f32_e32 v25, v24, v24
	v_add_f32_e32 v24, v29, v31
	v_fmac_f32_e32 v27, v26, v26
	v_add_f32_e32 v24, v24, v25
	v_add_f32_e32 v28, v27, v24
	v_pk_add_f32 v[22:23], v[22:23], v[194:195]
	v_pk_add_f32 v[20:21], v[20:21], v[192:193]
	v_pk_add_f32 v[24:25], v[16:17], v[196:197]
	v_mul_f32_e32 v16, v21, v21
	v_mul_f32_e32 v17, v23, v23
	v_pk_add_f32 v[26:27], v[18:19], v[198:199]
	v_mul_f32_e32 v18, v25, v25
	v_fmac_f32_e32 v16, v20, v20
	v_fmac_f32_e32 v17, v22, v22
	v_mul_f32_e32 v19, v27, v27
	v_fmac_f32_e32 v18, v24, v24
	v_add_f32_e32 v16, v16, v17
	v_add_f32_e32 v16, v16, v18
	v_fmac_f32_e32 v19, v26, v26
	v_add_f32_e32 v16, v19, v16
	v_add_f32_e32 v16, v28, v16
	ds_bpermute_b32 v17, v176, v16
	global_store_dwordx4 v[42:43], v[20:23], off offset:512
	global_store_dwordx4 v[42:43], v[24:27], off offset:528
	v_cvt_pk_bf16_f32 v18, v20, v21
	v_cvt_pk_bf16_f32 v19, v22, v23
	s_waitcnt lgkmcnt(0)
	v_add_f32_e32 v16, v16, v17
	ds_bpermute_b32 v17, v177, v16
	v_cvt_pk_bf16_f32 v20, v24, v25
	v_cvt_pk_bf16_f32 v21, v26, v27
	global_store_dwordx4 v[46:47], v[18:21], off offset:256
	s_and_saveexec_b64 s[50:51], s[6:7]
	s_cbranch_execz .LBB0_1446
	v_lshl_add_u64 v[18:19], v[32:33], 2, s[38:39]
	s_waitcnt lgkmcnt(0)
	v_add_f32_e32 v16, v16, v17
	global_atomic_add_f32 v[18:19], v16, off
.LBB0_1446:
	s_or_b64 exec, exec, s[50:51]
	v_or_b32_e32 v16, 0xb0, v148
	s_waitcnt lgkmcnt(0)
	v_ashrrev_i32_e32 v17, 31, v16
	v_lshlrev_b64 v[26:27], 13, v[16:17]
	v_lshl_add_u64 v[18:19], s[0:1], 0, v[26:27]
	v_lshl_add_u64 v[28:29], v[18:19], 0, v[146:147]
	v_lshlrev_b64 v[30:31], 12, v[16:17]
	v_lshl_add_u64 v[26:27], s[10:11], 0, v[26:27]
	v_lshl_add_u64 v[30:31], s[16:17], 0, v[30:31]
	v_lshl_add_u64 v[26:27], v[26:27], 0, v[146:147]
	v_lshl_add_u64 v[30:31], v[144:145], 1, v[30:31]
	s_waitcnt vmcnt(10)
	v_pk_add_f32 v[14:15], v[14:15], v[202:203]
	v_pk_add_f32 v[12:13], v[12:13], v[200:201]
	v_pk_add_f32 v[10:11], v[10:11], v[206:207]
	v_pk_add_f32 v[8:9], v[8:9], v[204:205]
	global_store_dwordx4 v[26:27], v[12:15], off
	global_store_dwordx4 v[26:27], v[8:11], off offset:16
	v_cvt_pk_bf16_f32 v18, v12, v13
	v_cvt_pk_bf16_f32 v19, v14, v15
	v_cvt_pk_bf16_f32 v20, v8, v9
	v_cvt_pk_bf16_f32 v21, v10, v11
	global_store_dwordx4 v[30:31], v[18:21], off
	s_nop 0
	v_mul_f32_e32 v13, v13, v13
	v_mul_f32_e32 v15, v15, v15
	v_mul_f32_e32 v9, v9, v9
	v_fmac_f32_e32 v13, v12, v12
	v_fmac_f32_e32 v15, v14, v14
	v_mul_f32_e32 v11, v11, v11
	v_fmac_f32_e32 v9, v8, v8
	v_add_f32_e32 v8, v13, v15
	v_fmac_f32_e32 v11, v10, v10
	v_add_f32_e32 v8, v8, v9
	v_add_f32_e32 v12, v11, v8
	v_pk_add_f32 v[6:7], v[6:7], v[210:211]
	v_pk_add_f32 v[4:5], v[4:5], v[208:209]
	v_pk_add_f32 v[8:9], v[0:1], v[212:213]
	v_mul_f32_e32 v0, v5, v5
	v_mul_f32_e32 v1, v7, v7
	v_pk_add_f32 v[10:11], v[2:3], v[214:215]
	v_mul_f32_e32 v2, v9, v9
	v_fmac_f32_e32 v0, v4, v4
	v_fmac_f32_e32 v1, v6, v6
	v_mul_f32_e32 v3, v11, v11
	v_fmac_f32_e32 v2, v8, v8
	v_add_f32_e32 v0, v0, v1
	v_add_f32_e32 v0, v0, v2
	v_fmac_f32_e32 v3, v10, v10
	v_add_f32_e32 v0, v3, v0
	v_add_f32_e32 v0, v12, v0
	ds_bpermute_b32 v1, v176, v0
	global_store_dwordx4 v[26:27], v[4:7], off offset:512
	global_store_dwordx4 v[26:27], v[8:11], off offset:528
	v_cvt_pk_bf16_f32 v2, v4, v5
	v_cvt_pk_bf16_f32 v3, v6, v7
	s_waitcnt lgkmcnt(0)
	v_add_f32_e32 v0, v0, v1
	ds_bpermute_b32 v1, v177, v0
	v_cvt_pk_bf16_f32 v4, v8, v9
	v_cvt_pk_bf16_f32 v5, v10, v11
	global_store_dwordx4 v[30:31], v[2:5], off offset:256
	s_and_saveexec_b64 s[50:51], s[6:7]
	s_cbranch_execz .LBB0_1448
	v_lshl_add_u64 v[2:3], v[16:17], 2, s[38:39]
	s_waitcnt lgkmcnt(0)
	v_add_f32_e32 v0, v0, v1
	global_atomic_add_f32 v[2:3], v0, off

.LBB0_1602:
	v_lshl_or_b32 v146, s44, 8, v149
	v_lshl_or_b32 v144, s46, 8, v150
	v_ashrrev_i32_e32 v147, 31, v146
	v_lshlrev_b64 v[162:163], 13, v[146:147]
	v_ashrrev_i32_e32 v145, 31, v144
	v_lshl_add_u64 v[154:155], s[0:1], 0, v[162:163]
	v_lshlrev_b64 v[144:145], 2, v[144:145]
	v_lshl_add_u64 v[164:165], v[154:155], 0, v[144:145]
	s_mov_b32 s98, 0x20000
	s_mov_b32 s99, 0
	s_mov_b32 s100, 0xa0000
	s_mov_b32 s101, 0
	global_load_dwordx4 v[184:187], v[164:165], off
	global_load_dwordx4 v[188:191], v[164:165], off offset:16
	global_load_dwordx4 v[192:195], v[164:165], off offset:512
	global_load_dwordx4 v[196:199], v[164:165], off offset:528
	v_lshl_add_u64 v[216:217], v[164:165], 0, s[98:99]
	global_load_dwordx4 v[200:203], v[216:217], off
	global_load_dwordx4 v[204:207], v[216:217], off offset:16
	global_load_dwordx4 v[208:211], v[216:217], off offset:512
	global_load_dwordx4 v[212:215], v[216:217], off offset:528
	v_lshl_add_u64 v[162:163], s[8:9], 0, v[162:163]
	v_lshl_add_u64 v[162:163], v[162:163], 0, v[144:145]
	s_waitcnt vmcnt(3)
	v_pk_add_f32 v[126:127], v[126:127], v[186:187]
	v_pk_add_f32 v[124:125], v[124:125], v[184:185]
	v_pk_add_f32 v[122:123], v[122:123], v[190:191]
	v_pk_add_f32 v[120:121], v[120:121], v[188:189]
	global_store_dwordx4 v[162:163], v[124:127], off
	global_store_dwordx4 v[162:163], v[120:123], off offset:16
	v_mul_f32_e32 v125, v125, v125
	v_mul_f32_e32 v127, v127, v127
	v_mul_f32_e32 v121, v121, v121
	v_fmac_f32_e32 v125, v124, v124
	v_fmac_f32_e32 v127, v126, v126
	v_mul_f32_e32 v123, v123, v123
	v_fmac_f32_e32 v121, v120, v120
	v_add_f32_e32 v120, v125, v127
	v_fmac_f32_e32 v123, v122, v122
	v_add_f32_e32 v120, v120, v121
	v_add_f32_e32 v124, v123, v120
	v_pk_add_f32 v[118:119], v[118:119], v[194:195]
	v_pk_add_f32 v[116:117], v[116:117], v[192:193]
	v_pk_add_f32 v[120:121], v[112:113], v[196:197]
	v_mul_f32_e32 v112, v117, v117
	v_mul_f32_e32 v113, v119, v119
	v_pk_add_f32 v[122:123], v[114:115], v[198:199]
	v_lshl_add_u64 v[216:217], v[216:217], 0, s[98:99]
	global_load_dwordx4 v[184:187], v[216:217], off
	global_load_dwordx4 v[188:191], v[216:217], off offset:16
	global_load_dwordx4 v[192:195], v[216:217], off offset:512
	global_load_dwordx4 v[196:199], v[216:217], off offset:528
	v_mul_f32_e32 v114, v121, v121
	v_fmac_f32_e32 v112, v116, v116
	v_fmac_f32_e32 v113, v118, v118
	v_mul_f32_e32 v115, v123, v123
	v_fmac_f32_e32 v114, v120, v120
	v_add_f32_e32 v112, v112, v113
	v_add_f32_e32 v112, v112, v114
	v_fmac_f32_e32 v115, v122, v122
	v_add_f32_e32 v112, v115, v112
	v_add_f32_e32 v112, v124, v112
	ds_bpermute_b32 v113, v176, v112
	global_store_dwordx4 v[162:163], v[116:119], off offset:512
	global_store_dwordx4 v[162:163], v[120:123], off offset:528
	s_waitcnt lgkmcnt(0)
	v_add_f32_e32 v112, v112, v113
	ds_bpermute_b32 v113, v177, v112
	s_and_saveexec_b64 s[44:45], s[4:5]
	s_cbranch_execz .LBB0_1604
	v_lshl_add_u64 v[114:115], v[146:147], 2, s[14:15]
	s_waitcnt lgkmcnt(0)
	v_add_f32_e32 v112, v112, v113
	global_atomic_add_f32 v[114:115], v112, off
.LBB0_1604:
	s_or_b64 exec, exec, s[44:45]
	v_or_b32_e32 v112, 16, v146
	s_waitcnt lgkmcnt(0)
	v_ashrrev_i32_e32 v113, 31, v112
	v_lshlrev_b64 v[122:123], 13, v[112:113]
	v_lshl_add_u64 v[114:115], s[0:1], 0, v[122:123]
	v_lshl_add_u64 v[124:125], v[114:115], 0, v[144:145]
	v_lshl_add_u64 v[122:123], s[8:9], 0, v[122:123]
	v_lshl_add_u64 v[122:123], v[122:123], 0, v[144:145]
	s_waitcnt vmcnt(8)
	v_pk_add_f32 v[110:111], v[110:111], v[202:203]
	v_pk_add_f32 v[108:109], v[108:109], v[200:201]
	v_pk_add_f32 v[106:107], v[106:107], v[206:207]
	v_pk_add_f32 v[104:105], v[104:105], v[204:205]
	global_store_dwordx4 v[122:123], v[108:111], off
	global_store_dwordx4 v[122:123], v[104:107], off offset:16
	v_mul_f32_e32 v109, v109, v109
	v_mul_f32_e32 v111, v111, v111
	v_mul_f32_e32 v105, v105, v105
	v_fmac_f32_e32 v109, v108, v108
	v_fmac_f32_e32 v111, v110, v110
	v_mul_f32_e32 v107, v107, v107
	v_fmac_f32_e32 v105, v104, v104
	v_add_f32_e32 v104, v109, v111
	v_fmac_f32_e32 v107, v106, v106
	v_add_f32_e32 v104, v104, v105
	v_add_f32_e32 v108, v107, v104
	v_pk_add_f32 v[102:103], v[102:103], v[210:211]
	v_pk_add_f32 v[100:101], v[100:101], v[208:209]
	v_pk_add_f32 v[104:105], v[96:97], v[212:213]
	v_mul_f32_e32 v96, v101, v101
	v_mul_f32_e32 v97, v103, v103
	v_pk_add_f32 v[106:107], v[98:99], v[214:215]
	v_lshl_add_u64 v[216:217], v[216:217], 0, s[98:99]
	global_load_dwordx4 v[200:203], v[216:217], off
	global_load_dwordx4 v[204:207], v[216:217], off offset:16
	global_load_dwordx4 v[208:211], v[216:217], off offset:512
	global_load_dwordx4 v[212:215], v[216:217], off offset:528
	v_mul_f32_e32 v98, v105, v105
	v_fmac_f32_e32 v96, v100, v100
	v_fmac_f32_e32 v97, v102, v102
	v_mul_f32_e32 v99, v107, v107
	v_fmac_f32_e32 v98, v104, v104
	v_add_f32_e32 v96, v96, v97
	v_add_f32_e32 v96, v96, v98
	v_fmac_f32_e32 v99, v106, v106
	v_add_f32_e32 v96, v99, v96
	v_add_f32_e32 v96, v108, v96
	ds_bpermute_b32 v97, v176, v96
	global_store_dwordx4 v[122:123], v[100:103], off offset:512
	global_store_dwordx4 v[122:123], v[104:107], off offset:528
	s_waitcnt lgkmcnt(0)
	v_add_f32_e32 v96, v96, v97
	ds_bpermute_b32 v97, v177, v96
	s_and_saveexec_b64 s[44:45], s[4:5]
	s_cbranch_execz .LBB0_1606
	v_lshl_add_u64 v[98:99], v[112:113], 2, s[14:15]
	s_waitcnt lgkmcnt(0)
	v_add_f32_e32 v96, v96, v97
	global_atomic_add_f32 v[98:99], v96, off
.LBB0_1606:
	s_or_b64 exec, exec, s[44:45]
	v_or_b32_e32 v96, 32, v146
	s_waitcnt lgkmcnt(0)
	v_ashrrev_i32_e32 v97, 31, v96
	v_lshlrev_b64 v[106:107], 13, v[96:97]
	v_lshl_add_u64 v[98:99], s[0:1], 0, v[106:107]
	v_lshl_add_u64 v[108:109], v[98:99], 0, v[144:145]
	v_lshl_add_u64 v[106:107], s[8:9], 0, v[106:107]
	v_lshl_add_u64 v[106:107], v[106:107], 0, v[144:145]
	s_waitcnt vmcnt(11)
	v_pk_add_f32 v[94:95], v[94:95], v[186:187]
	v_pk_add_f32 v[92:93], v[92:93], v[184:185]
	v_pk_add_f32 v[90:91], v[90:91], v[190:191]
	v_pk_add_f32 v[88:89], v[88:89], v[188:189]
	global_store_dwordx4 v[106:107], v[92:95], off
	global_store_dwordx4 v[106:107], v[88:91], off offset:16
	v_mul_f32_e32 v93, v93, v93
	v_mul_f32_e32 v95, v95, v95
	v_mul_f32_e32 v89, v89, v89
	v_fmac_f32_e32 v93, v92, v92
	v_fmac_f32_e32 v95, v94, v94
	v_mul_f32_e32 v91, v91, v91
	v_fmac_f32_e32 v89, v88, v88
	v_add_f32_e32 v88, v93, v95
	v_fmac_f32_e32 v91, v90, v90
	v_add_f32_e32 v88, v88, v89
	v_add_f32_e32 v92, v91, v88
	v_pk_add_f32 v[86:87], v[86:87], v[194:195]
	v_pk_add_f32 v[84:85], v[84:85], v[192:193]
	v_pk_add_f32 v[88:89], v[80:81], v[196:197]
	v_mul_f32_e32 v80, v85, v85
	v_mul_f32_e32 v81, v87, v87
	v_pk_add_f32 v[90:91], v[82:83], v[198:199]
	v_lshl_add_u64 v[216:217], v[216:217], 0, s[100:101]
	global_load_dwordx4 v[184:187], v[216:217], off
	global_load_dwordx4 v[188:191], v[216:217], off offset:16
	global_load_dwordx4 v[192:195], v[216:217], off offset:512
	global_load_dwordx4 v[196:199], v[216:217], off offset:528
	v_mul_f32_e32 v82, v89, v89
	v_fmac_f32_e32 v80, v84, v84
	v_fmac_f32_e32 v81, v86, v86
	v_mul_f32_e32 v83, v91, v91
	v_fmac_f32_e32 v82, v88, v88
	v_add_f32_e32 v80, v80, v81
	v_add_f32_e32 v80, v80, v82
	v_fmac_f32_e32 v83, v90, v90
	v_add_f32_e32 v80, v83, v80
	v_add_f32_e32 v80, v92, v80
	ds_bpermute_b32 v81, v176, v80
	global_store_dwordx4 v[106:107], v[84:87], off offset:512
	global_store_dwordx4 v[106:107], v[88:91], off offset:528
	s_waitcnt lgkmcnt(0)
	v_add_f32_e32 v80, v80, v81
	ds_bpermute_b32 v81, v177, v80
	s_and_saveexec_b64 s[44:45], s[4:5]
	s_cbranch_execz .LBB0_1608
	v_lshl_add_u64 v[82:83], v[96:97], 2, s[14:15]
	s_waitcnt lgkmcnt(0)
	v_add_f32_e32 v80, v80, v81
	global_atomic_add_f32 v[82:83], v80, off
.LBB0_1608:
	s_or_b64 exec, exec, s[44:45]
	v_or_b32_e32 v80, 48, v146
	s_waitcnt lgkmcnt(0)
	v_ashrrev_i32_e32 v81, 31, v80
	v_lshlrev_b64 v[90:91], 13, v[80:81]
	v_lshl_add_u64 v[82:83], s[0:1], 0, v[90:91]
	v_lshl_add_u64 v[92:93], v[82:83], 0, v[144:145]
	v_lshl_add_u64 v[90:91], s[8:9], 0, v[90:91]
	v_lshl_add_u64 v[90:91], v[90:91], 0, v[144:145]
	s_waitcnt vmcnt(11)
	v_pk_add_f32 v[78:79], v[78:79], v[202:203]
	v_pk_add_f32 v[76:77], v[76:77], v[200:201]
	v_pk_add_f32 v[74:75], v[74:75], v[206:207]
	v_pk_add_f32 v[72:73], v[72:73], v[204:205]
	global_store_dwordx4 v[90:91], v[76:79], off
	global_store_dwordx4 v[90:91], v[72:75], off offset:16
	v_mul_f32_e32 v77, v77, v77
	v_mul_f32_e32 v79, v79, v79
	v_mul_f32_e32 v73, v73, v73
	v_fmac_f32_e32 v77, v76, v76
	v_fmac_f32_e32 v79, v78, v78
	v_mul_f32_e32 v75, v75, v75
	v_fmac_f32_e32 v73, v72, v72
	v_add_f32_e32 v72, v77, v79
	v_fmac_f32_e32 v75, v74, v74
	v_add_f32_e32 v72, v72, v73
	v_add_f32_e32 v76, v75, v72
	v_pk_add_f32 v[70:71], v[70:71], v[210:211]
	v_pk_add_f32 v[68:69], v[68:69], v[208:209]
	v_pk_add_f32 v[72:73], v[64:65], v[212:213]
	v_mul_f32_e32 v64, v69, v69
	v_mul_f32_e32 v65, v71, v71
	v_pk_add_f32 v[74:75], v[66:67], v[214:215]
	v_lshl_add_u64 v[216:217], v[216:217], 0, s[98:99]
	global_load_dwordx4 v[200:203], v[216:217], off
	global_load_dwordx4 v[204:207], v[216:217], off offset:16
	global_load_dwordx4 v[208:211], v[216:217], off offset:512
	global_load_dwordx4 v[212:215], v[216:217], off offset:528
	v_mul_f32_e32 v66, v73, v73
	v_fmac_f32_e32 v64, v68, v68
	v_fmac_f32_e32 v65, v70, v70
	v_mul_f32_e32 v67, v75, v75
	v_fmac_f32_e32 v66, v72, v72
	v_add_f32_e32 v64, v64, v65
	v_add_f32_e32 v64, v64, v66
	v_fmac_f32_e32 v67, v74, v74
	v_add_f32_e32 v64, v67, v64
	v_add_f32_e32 v64, v76, v64
	ds_bpermute_b32 v65, v176, v64
	global_store_dwordx4 v[90:91], v[68:71], off offset:512
	global_store_dwordx4 v[90:91], v[72:75], off offset:528
	s_waitcnt lgkmcnt(0)
	v_add_f32_e32 v64, v64, v65
	ds_bpermute_b32 v65, v177, v64
	s_and_saveexec_b64 s[44:45], s[4:5]
	s_cbranch_execz .LBB0_1610
	v_lshl_add_u64 v[66:67], v[80:81], 2, s[14:15]
	s_waitcnt lgkmcnt(0)
	v_add_f32_e32 v64, v64, v65
	global_atomic_add_f32 v[66:67], v64, off
.LBB0_1610:
	s_or_b64 exec, exec, s[44:45]
	v_or_b32_e32 v64, 0x80, v146
	s_waitcnt lgkmcnt(0)
	v_ashrrev_i32_e32 v65, 31, v64
	v_lshlrev_b64 v[74:75], 13, v[64:65]
	v_lshl_add_u64 v[66:67], s[0:1], 0, v[74:75]
	v_lshl_add_u64 v[76:77], v[66:67], 0, v[144:145]
	v_lshl_add_u64 v[74:75], s[8:9], 0, v[74:75]
	v_lshl_add_u64 v[74:75], v[74:75], 0, v[144:145]
	s_waitcnt vmcnt(11)
	v_pk_add_f32 v[62:63], v[62:63], v[186:187]
	v_pk_add_f32 v[60:61], v[60:61], v[184:185]
	v_pk_add_f32 v[58:59], v[58:59], v[190:191]
	v_pk_add_f32 v[56:57], v[56:57], v[188:189]
	global_store_dwordx4 v[74:75], v[60:63], off
	global_store_dwordx4 v[74:75], v[56:59], off offset:16
	v_mul_f32_e32 v61, v61, v61
	v_mul_f32_e32 v63, v63, v63
	v_mul_f32_e32 v57, v57, v57
	v_fmac_f32_e32 v61, v60, v60
	v_fmac_f32_e32 v63, v62, v62
	v_mul_f32_e32 v59, v59, v59
	v_fmac_f32_e32 v57, v56, v56
	v_add_f32_e32 v56, v61, v63
	v_fmac_f32_e32 v59, v58, v58
	v_add_f32_e32 v56, v56, v57
	v_add_f32_e32 v60, v59, v56
	v_pk_add_f32 v[54:55], v[54:55], v[194:195]
	v_pk_add_f32 v[52:53], v[52:53], v[192:193]
	v_pk_add_f32 v[56:57], v[48:49], v[196:197]
	v_mul_f32_e32 v48, v53, v53
	v_mul_f32_e32 v49, v55, v55
	v_pk_add_f32 v[58:59], v[50:51], v[198:199]
	v_lshl_add_u64 v[216:217], v[216:217], 0, s[98:99]
	global_load_dwordx4 v[184:187], v[216:217], off
	global_load_dwordx4 v[188:191], v[216:217], off offset:16
	global_load_dwordx4 v[192:195], v[216:217], off offset:512
	global_load_dwordx4 v[196:199], v[216:217], off offset:528
	v_mul_f32_e32 v50, v57, v57
	v_fmac_f32_e32 v48, v52, v52
	v_fmac_f32_e32 v49, v54, v54
	v_mul_f32_e32 v51, v59, v59
	v_fmac_f32_e32 v50, v56, v56
	v_add_f32_e32 v48, v48, v49
	v_add_f32_e32 v48, v48, v50
	v_fmac_f32_e32 v51, v58, v58
	v_add_f32_e32 v48, v51, v48
	v_add_f32_e32 v48, v60, v48
	ds_bpermute_b32 v49, v176, v48
	global_store_dwordx4 v[74:75], v[52:55], off offset:512
	global_store_dwordx4 v[74:75], v[56:59], off offset:528
	s_waitcnt lgkmcnt(0)
	v_add_f32_e32 v48, v48, v49
	ds_bpermute_b32 v49, v177, v48
	s_and_saveexec_b64 s[44:45], s[4:5]
	s_cbranch_execz .LBB0_1612
	v_lshl_add_u64 v[50:51], v[64:65], 2, s[14:15]
	s_waitcnt lgkmcnt(0)
	v_add_f32_e32 v48, v48, v49
	global_atomic_add_f32 v[50:51], v48, off
.LBB0_1612:
	s_or_b64 exec, exec, s[44:45]
	v_or_b32_e32 v48, 0x90, v146
	s_waitcnt lgkmcnt(0)
	v_ashrrev_i32_e32 v49, 31, v48
	v_lshlrev_b64 v[58:59], 13, v[48:49]
	v_lshl_add_u64 v[50:51], s[0:1], 0, v[58:59]
	v_lshl_add_u64 v[60:61], v[50:51], 0, v[144:145]
	v_lshl_add_u64 v[58:59], s[8:9], 0, v[58:59]
	v_lshl_add_u64 v[58:59], v[58:59], 0, v[144:145]
	s_waitcnt vmcnt(11)
	v_pk_add_f32 v[46:47], v[46:47], v[202:203]
	v_pk_add_f32 v[44:45], v[44:45], v[200:201]
	v_pk_add_f32 v[42:43], v[42:43], v[206:207]
	v_pk_add_f32 v[40:41], v[40:41], v[204:205]
	global_store_dwordx4 v[58:59], v[44:47], off
	global_store_dwordx4 v[58:59], v[40:43], off offset:16
	v_mul_f32_e32 v45, v45, v45
	v_mul_f32_e32 v47, v47, v47
	v_mul_f32_e32 v41, v41, v41
	v_fmac_f32_e32 v45, v44, v44
	v_fmac_f32_e32 v47, v46, v46
	v_mul_f32_e32 v43, v43, v43
	v_fmac_f32_e32 v41, v40, v40
	v_add_f32_e32 v40, v45, v47
	v_fmac_f32_e32 v43, v42, v42
	v_add_f32_e32 v40, v40, v41
	v_add_f32_e32 v44, v43, v40
	v_pk_add_f32 v[38:39], v[38:39], v[210:211]
	v_pk_add_f32 v[36:37], v[36:37], v[208:209]
	v_pk_add_f32 v[40:41], v[32:33], v[212:213]
	v_mul_f32_e32 v32, v37, v37
	v_mul_f32_e32 v33, v39, v39
	v_pk_add_f32 v[42:43], v[34:35], v[214:215]
	v_lshl_add_u64 v[216:217], v[216:217], 0, s[98:99]
	global_load_dwordx4 v[200:203], v[216:217], off
	global_load_dwordx4 v[204:207], v[216:217], off offset:16
	global_load_dwordx4 v[208:211], v[216:217], off offset:512
	global_load_dwordx4 v[212:215], v[216:217], off offset:528
	v_mul_f32_e32 v34, v41, v41
	v_fmac_f32_e32 v32, v36, v36
	v_fmac_f32_e32 v33, v38, v38
	v_mul_f32_e32 v35, v43, v43
	v_fmac_f32_e32 v34, v40, v40
	v_add_f32_e32 v32, v32, v33
	v_add_f32_e32 v32, v32, v34
	v_fmac_f32_e32 v35, v42, v42
	v_add_f32_e32 v32, v35, v32
	v_add_f32_e32 v32, v44, v32
	ds_bpermute_b32 v33, v176, v32
	global_store_dwordx4 v[58:59], v[36:39], off offset:512
	global_store_dwordx4 v[58:59], v[40:43], off offset:528
	s_waitcnt lgkmcnt(0)
	v_add_f32_e32 v32, v32, v33
	ds_bpermute_b32 v33, v177, v32
	s_and_saveexec_b64 s[44:45], s[4:5]
	s_cbranch_execz .LBB0_1614
	v_lshl_add_u64 v[34:35], v[48:49], 2, s[14:15]
	s_waitcnt lgkmcnt(0)
	v_add_f32_e32 v32, v32, v33
	global_atomic_add_f32 v[34:35], v32, off
.LBB0_1614:
	s_or_b64 exec, exec, s[44:45]
	v_or_b32_e32 v32, 0xa0, v146
	s_waitcnt lgkmcnt(0)
	v_ashrrev_i32_e32 v33, 31, v32
	v_lshlrev_b64 v[42:43], 13, v[32:33]
	v_lshl_add_u64 v[34:35], s[0:1], 0, v[42:43]
	v_lshl_add_u64 v[44:45], v[34:35], 0, v[144:145]
	v_lshl_add_u64 v[42:43], s[8:9], 0, v[42:43]
	v_lshl_add_u64 v[42:43], v[42:43], 0, v[144:145]
	s_waitcnt vmcnt(11)
	v_pk_add_f32 v[30:31], v[30:31], v[186:187]
	v_pk_add_f32 v[28:29], v[28:29], v[184:185]
	v_pk_add_f32 v[26:27], v[26:27], v[190:191]
	v_pk_add_f32 v[24:25], v[24:25], v[188:189]
	global_store_dwordx4 v[42:43], v[28:31], off
	global_store_dwordx4 v[42:43], v[24:27], off offset:16
	v_mul_f32_e32 v29, v29, v29
	v_mul_f32_e32 v31, v31, v31
	v_mul_f32_e32 v25, v25, v25
	v_fmac_f32_e32 v29, v28, v28
	v_fmac_f32_e32 v31, v30, v30
	v_mul_f32_e32 v27, v27, v27
	v_fmac_f32_e32 v25, v24, v24
	v_add_f32_e32 v24, v29, v31
	v_fmac_f32_e32 v27, v26, v26
	v_add_f32_e32 v24, v24, v25
	v_add_f32_e32 v28, v27, v24
	v_pk_add_f32 v[22:23], v[22:23], v[194:195]
	v_pk_add_f32 v[20:21], v[20:21], v[192:193]
	v_pk_add_f32 v[24:25], v[16:17], v[196:197]
	v_mul_f32_e32 v16, v21, v21
	v_mul_f32_e32 v17, v23, v23
	v_pk_add_f32 v[26:27], v[18:19], v[198:199]
	v_mul_f32_e32 v18, v25, v25
	v_fmac_f32_e32 v16, v20, v20
	v_fmac_f32_e32 v17, v22, v22
	v_mul_f32_e32 v19, v27, v27
	v_fmac_f32_e32 v18, v24, v24
	v_add_f32_e32 v16, v16, v17
	v_add_f32_e32 v16, v16, v18
	v_fmac_f32_e32 v19, v26, v26
	v_add_f32_e32 v16, v19, v16
	v_add_f32_e32 v16, v28, v16
	ds_bpermute_b32 v17, v176, v16
	global_store_dwordx4 v[42:43], v[20:23], off offset:512
	global_store_dwordx4 v[42:43], v[24:27], off offset:528
	s_waitcnt lgkmcnt(0)
	v_add_f32_e32 v16, v16, v17
	ds_bpermute_b32 v17, v177, v16
	s_and_saveexec_b64 s[44:45], s[4:5]
	s_cbranch_execz .LBB0_1616
	v_lshl_add_u64 v[18:19], v[32:33], 2, s[14:15]
	s_waitcnt lgkmcnt(0)
	v_add_f32_e32 v16, v16, v17
	global_atomic_add_f32 v[18:19], v16, off
.LBB0_1616:
	s_or_b64 exec, exec, s[44:45]
	v_or_b32_e32 v16, 0xb0, v146
	s_waitcnt lgkmcnt(0)
	v_ashrrev_i32_e32 v17, 31, v16
	v_lshlrev_b64 v[26:27], 13, v[16:17]
	v_lshl_add_u64 v[18:19], s[0:1], 0, v[26:27]
	v_lshl_add_u64 v[28:29], v[18:19], 0, v[144:145]
	v_lshl_add_u64 v[26:27], s[8:9], 0, v[26:27]
	v_lshl_add_u64 v[26:27], v[26:27], 0, v[144:145]
	s_waitcnt vmcnt(7)
	v_pk_add_f32 v[14:15], v[14:15], v[202:203]
	v_pk_add_f32 v[12:13], v[12:13], v[200:201]
	v_pk_add_f32 v[10:11], v[10:11], v[206:207]
	v_pk_add_f32 v[8:9], v[8:9], v[204:205]
	global_store_dwordx4 v[26:27], v[12:15], off
	global_store_dwordx4 v[26:27], v[8:11], off offset:16
	v_mul_f32_e32 v13, v13, v13
	v_mul_f32_e32 v15, v15, v15
	v_mul_f32_e32 v9, v9, v9
	v_fmac_f32_e32 v13, v12, v12
	v_fmac_f32_e32 v15, v14, v14
	v_mul_f32_e32 v11, v11, v11
	v_fmac_f32_e32 v9, v8, v8
	v_add_f32_e32 v8, v13, v15
	v_fmac_f32_e32 v11, v10, v10
	v_add_f32_e32 v8, v8, v9
	v_add_f32_e32 v12, v11, v8
	v_pk_add_f32 v[6:7], v[6:7], v[210:211]
	v_pk_add_f32 v[4:5], v[4:5], v[208:209]
	v_pk_add_f32 v[8:9], v[0:1], v[212:213]
	v_mul_f32_e32 v0, v5, v5
	v_mul_f32_e32 v1, v7, v7
	v_pk_add_f32 v[10:11], v[2:3], v[214:215]
	v_mul_f32_e32 v2, v9, v9
	v_fmac_f32_e32 v0, v4, v4
	v_fmac_f32_e32 v1, v6, v6
	v_mul_f32_e32 v3, v11, v11
	v_fmac_f32_e32 v2, v8, v8
	v_add_f32_e32 v0, v0, v1
	v_add_f32_e32 v0, v0, v2
	v_fmac_f32_e32 v3, v10, v10
	v_add_f32_e32 v0, v3, v0
	v_add_f32_e32 v0, v12, v0
	ds_bpermute_b32 v1, v176, v0
	global_store_dwordx4 v[26:27], v[4:7], off offset:512
	global_store_dwordx4 v[26:27], v[8:11], off offset:528
	s_waitcnt lgkmcnt(0)
	v_add_f32_e32 v0, v0, v1
	ds_bpermute_b32 v1, v177, v0
	s_and_saveexec_b64 s[44:45], s[4:5]
	s_cbranch_execz .LBB0_1618
	v_lshl_add_u64 v[2:3], v[16:17], 2, s[14:15]
	s_waitcnt lgkmcnt(0)
	v_add_f32_e32 v0, v0, v1
	global_atomic_add_f32 v[2:3], v0, off

	.amdhsa_kernel _Z8yoco_fwd4Args
		.amdhsa_group_segment_fixed_size 0
		.amdhsa_private_segment_fixed_size 0
		.amdhsa_kernarg_size 440
		.amdhsa_user_sgpr_count 2
		.amdhsa_user_sgpr_dispatch_ptr 0
		.amdhsa_user_sgpr_queue_ptr 0
		.amdhsa_user_sgpr_kernarg_segment_ptr 1
		.amdhsa_user_sgpr_dispatch_id 0
		.amdhsa_user_sgpr_kernarg_preload_length 0
		.amdhsa_user_sgpr_kernarg_preload_offset 0
		.amdhsa_user_sgpr_private_segment_size 0
		.amdhsa_uses_dynamic_stack 0
		.amdhsa_enable_private_segment 0
		.amdhsa_system_sgpr_workgroup_id_x 1
		.amdhsa_system_sgpr_workgroup_id_y 0
		.amdhsa_system_sgpr_workgroup_id_z 0
		.amdhsa_system_sgpr_workgroup_info 0
		.amdhsa_system_vgpr_workitem_id 2
		.amdhsa_next_free_vgpr 256
		.amdhsa_next_free_sgpr 102
		.amdhsa_accum_offset 256
		.amdhsa_reserve_vcc 1
		.amdhsa_float_round_mode_32 0
		.amdhsa_float_round_mode_16_64 0
		.amdhsa_float_denorm_mode_32 3
		.amdhsa_float_denorm_mode_16_64 3
		.amdhsa_dx10_clamp 1
		.amdhsa_ieee_mode 1
		.amdhsa_fp16_overflow 0
		.amdhsa_tg_split 0
		.amdhsa_exception_fp_ieee_invalid_op 0
		.amdhsa_exception_fp_denorm_src 0
		.amdhsa_exception_fp_ieee_div_zero 0
		.amdhsa_exception_fp_ieee_overflow 0
		.amdhsa_exception_fp_ieee_underflow 0
		.amdhsa_exception_fp_ieee_inexact 0
		.amdhsa_exception_int_div_zero 0
	.end_amdhsa_kernel

amdhsa.kernels:
  - .agpr_count:     0
    .args:
      - .offset:         0
        .size:           184
        .value_kind:     by_value
      - .offset:         184
        .size:           4
        .value_kind:     hidden_block_count_x
      - .offset:         188
        .size:           4
        .value_kind:     hidden_block_count_y
      - .offset:         192
        .size:           4
        .value_kind:     hidden_block_count_z
      - .offset:         196
        .size:           2
        .value_kind:     hidden_group_size_x
      - .offset:         198
        .size:           2
        .value_kind:     hidden_group_size_y
      - .offset:         200
        .size:           2
        .value_kind:     hidden_group_size_z
      - .offset:         202
        .size:           2
        .value_kind:     hidden_remainder_x
      - .offset:         204
        .size:           2
        .value_kind:     hidden_remainder_y
      - .offset:         206
        .size:           2
        .value_kind:     hidden_remainder_z
      - .offset:         224
        .size:           8
        .value_kind:     hidden_global_offset_x
      - .offset:         232
        .size:           8
        .value_kind:     hidden_global_offset_y
      - .offset:         240
        .size:           8
        .value_kind:     hidden_global_offset_z
      - .offset:         248
        .size:           2
        .value_kind:     hidden_grid_dims
      - .offset:         272
        .size:           8
        .value_kind:     hidden_multigrid_sync_arg
      - .offset:         304
        .size:           4
        .value_kind:     hidden_dynamic_lds_size
    .group_segment_fixed_size: 0
    .kernarg_segment_align: 8
    .kernarg_segment_size: 440
    .language:       OpenCL C
    .language_version:
      - 2
      - 0
    .max_flat_workgroup_size: 512
    .name:           _Z8yoco_fwd4Args
    .private_segment_fixed_size: 0
    .sgpr_count:     108
    .sgpr_spill_count: 35
    .symbol:         _Z8yoco_fwd4Args.kd
    .uniform_work_group_size: 1
    .uses_dynamic_stack: false
    .vgpr_count:     256
    .vgpr_spill_count: 0
    .wavefront_size: 64
